# GEMM: s_setprio 1 held during the LDS-read/DMA-issue phase (after barrier 2) and dropped before the vmcnt wait, instead of around the MFMA cluster
# baseline (speedup 1.0000x reference)
; #define PG8_STAGE(bufoff, gbase, voff) do { _Pragma("unroll") for (int _i = 0; _i < 2; ++_i) \
;         __builtin_amdgcn_global_load_lds((const unsigned*)((const char*)(gbase) + (voff)[_i]), (PG8_LAS unsigned*)(lds + (bufoff) + ldsw + _i * 8192), 16, 0, 0); } while (0)
; #define PG8_LDA(dst, b, h) do { _Pragma("unroll") for (int m = 0; m < 4; ++m) _Pragma("unroll") for (int k = 0; k < 2; ++k) dst[m][k] = *(const PG8_LAS bf16x8*)(lds + PG8_SA(b, h) + aoff + m * 2048 + k * 1024); } while (0)
; #define PG8_LDB(dst, b, h) do { _Pragma("unroll") for (int n = 0; n < 2; ++n) _Pragma("unroll") for (int k = 0; k < 2; ++k) dst[n][k] = *(const PG8_LAS bf16x8*)(lds + PG8_SB(b, h) + boff + n * 2048 + k * 1024); } while (0)
; #define PG8_MMA(ai, bj, At, Bt) do { __builtin_amdgcn_s_setprio(1); _Pragma("unroll") for (int m = 0; m < 4; ++m) _Pragma("unroll") for (int n = 0; n < 2; ++n) _Pragma("unroll") for (int k = 0; k < 2; ++k) \
;         acc[ai][bj][m][n] = __builtin_amdgcn_mfma_f32_16x16x32_bf16(Bt[n][k], At[m][k], acc[ai][bj][m][n], 0, 0, 0); __builtin_amdgcn_s_setprio(0); } while (0)
; #define PG8_WAIT_V(n) asm volatile("s_waitcnt vmcnt(" #n ")" ::: "memory")
; #define PG8_WAIT_L(n) asm volatile("s_waitcnt lgkmcnt(" #n ")" ::: "memory")
; #define PG8_BAR __builtin_amdgcn_s_barrier()
; #define PG8_SCHED __builtin_amdgcn_sched_barrier(0)
; template <class Epi, class Sched, bool ALIGN_EPI = false, bool SP2 = false>
; __device__ __forceinline__ void gemm_phase(PG8_LAS unsigned char* lds, const Gemm g, const Sched& S, const Epi& E) {
;     ...
;             PG8_LDB(B0, 0, 0); PG8_LDB(B1, 0, 1); PG8_SCHED; PG8_LDA(At, 0, 0); PG8_STAGE(PG8_SA(1, 1), a1 + hstep, voffA);
;             PG8_WAIT_V(8); PG8_WAIT_L(0); PG8_BAR; PG8_MMA(0, 0, At, B0); PG8_MMA(0, 1, At, B1); PG8_BAR; PG8_SCHED;
;             PG8_LDA(At, 0, 1); PG8_STAGE(PG8_SB(0, 0), b2, voffB); PG8_STAGE(PG8_SB(0, 1), b2 + hstep, voffB); PG8_STAGE(PG8_SA(0, 0), a2, voffA);
;             PG8_WAIT_V(8); PG8_WAIT_L(0); PG8_BAR; PG8_MMA(1, 0, At, B0); PG8_MMA(1, 1, At, B1); PG8_BAR; PG8_SCHED;
.LBB0_180:
	s_add_u32 s6, s4, 0xfffc0080
	s_addc_u32 s7, s5, -1
	s_add_i32 s34, 0, 0x10000
	s_cmp_eq_u32 s49, 12
	s_cselect_b32 s43, s15, s7
	s_cselect_b32 s42, s26, s6
	s_cselect_b32 s7, s27, s47
	s_cselect_b32 s6, s44, s45
	s_add_i32 s35, 0, 0x14000
	v_add_u32_e32 v158, s34, v152
	v_add_u32_e32 v174, s35, v152
	ds_read_b128 v[144:147], v158
	ds_read_b128 v[148:151], v158 offset:1024
	ds_read_b128 v[154:157], v158 offset:2048
	ds_read_b128 v[158:161], v158 offset:3072
	ds_read_b128 v[162:165], v174
	ds_read_b128 v[166:169], v174 offset:1024
	ds_read_b128 v[170:173], v174 offset:2048
	ds_read_b128 v[174:177], v174 offset:3072
	v_lshl_add_u64 v[178:179], s[4:5], 0, v[140:141]
	s_add_i32 m0, s18, 0xc000
	ds_read_b128 v[184:187], v153
	ds_read_b128 v[188:191], v153 offset:1024
	ds_read_b128 v[192:195], v153 offset:2048
	ds_read_b128 v[196:199], v153 offset:3072
	ds_read_b128 v[210:213], v153 offset:4096
	ds_read_b128 v[214:217], v153 offset:5120
	ds_read_b128 v[218:221], v153 offset:6144
	ds_read_b128 v[222:225], v153 offset:7168
	global_load_lds_dwordx4 v[178:179], off
	v_lshl_add_u64 v[178:179], s[4:5], 0, v[142:143]
	s_add_i32 m0, s18, 0xe000
	s_nop 0
	global_load_lds_dwordx4 v[178:179], off
	s_setprio 0
	s_waitcnt vmcnt(8)
	s_waitcnt lgkmcnt(0)
	s_barrier
	s_waitcnt lgkmcnt(0)
	v_mfma_f32_16x16x32_bf16 v[124:127], v[144:147], v[184:187], v[124:127]
	v_mfma_f32_16x16x32_bf16 v[120:123], v[154:157], v[184:187], v[120:123]
	v_mfma_f32_16x16x32_bf16 v[108:111], v[144:147], v[192:195], v[108:111]
	v_mfma_f32_16x16x32_bf16 v[104:107], v[154:157], v[192:195], v[104:107]
	v_mfma_f32_16x16x32_bf16 v[92:95], v[144:147], v[210:213], v[92:95]
	v_mfma_f32_16x16x32_bf16 v[88:91], v[154:157], v[210:213], v[88:91]
	v_mfma_f32_16x16x32_bf16 v[76:79], v[144:147], v[218:221], v[76:79]
	v_mfma_f32_16x16x32_bf16 v[72:75], v[154:157], v[218:221], v[72:75]
	v_mfma_f32_16x16x32_bf16 v[124:127], v[148:151], v[188:191], v[124:127]
	v_mfma_f32_16x16x32_bf16 v[120:123], v[158:161], v[188:191], v[120:123]
	v_mfma_f32_16x16x32_bf16 v[108:111], v[148:151], v[196:199], v[108:111]
	v_mfma_f32_16x16x32_bf16 v[104:107], v[158:161], v[196:199], v[104:107]
	v_mfma_f32_16x16x32_bf16 v[92:95], v[148:151], v[214:217], v[92:95]
	v_mfma_f32_16x16x32_bf16 v[88:91], v[158:161], v[214:217], v[88:91]
	v_mfma_f32_16x16x32_bf16 v[76:79], v[148:151], v[222:225], v[76:79]
	v_mfma_f32_16x16x32_bf16 v[72:75], v[158:161], v[222:225], v[72:75]
	v_mfma_f32_16x16x32_bf16 v[116:119], v[162:165], v[184:187], v[116:119]
	v_mfma_f32_16x16x32_bf16 v[112:115], v[170:173], v[184:187], v[112:115]
	v_mfma_f32_16x16x32_bf16 v[100:103], v[162:165], v[192:195], v[100:103]
	v_mfma_f32_16x16x32_bf16 v[96:99], v[170:173], v[192:195], v[96:99]
	v_mfma_f32_16x16x32_bf16 v[84:87], v[162:165], v[210:213], v[84:87]
	v_mfma_f32_16x16x32_bf16 v[80:83], v[170:173], v[210:213], v[80:83]
	v_mfma_f32_16x16x32_bf16 v[68:71], v[162:165], v[218:221], v[68:71]
	v_mfma_f32_16x16x32_bf16 v[64:67], v[170:173], v[218:221], v[64:67]
	v_mfma_f32_16x16x32_bf16 v[116:119], v[166:169], v[188:191], v[116:119]
	v_mfma_f32_16x16x32_bf16 v[112:115], v[174:177], v[188:191], v[112:115]
	v_mfma_f32_16x16x32_bf16 v[100:103], v[166:169], v[196:199], v[100:103]
	v_mfma_f32_16x16x32_bf16 v[96:99], v[174:177], v[196:199], v[96:99]
	v_mfma_f32_16x16x32_bf16 v[84:87], v[166:169], v[214:217], v[84:87]
	v_mfma_f32_16x16x32_bf16 v[80:83], v[174:177], v[214:217], v[80:83]
	v_mfma_f32_16x16x32_bf16 v[68:71], v[166:169], v[222:225], v[68:71]
	v_mfma_f32_16x16x32_bf16 v[64:67], v[174:177], v[222:225], v[64:67]
	s_barrier
	s_setprio 1
	s_add_i32 s34, s34, s17
	v_lshl_add_u64 v[178:179], s[6:7], 0, v[132:133]
	s_mov_b32 m0, s34
	ds_read_b128 v[184:187], v153 offset:16384
	ds_read_b128 v[188:191], v153 offset:17408
	ds_read_b128 v[192:195], v153 offset:18432
	ds_read_b128 v[196:199], v153 offset:19456
	ds_read_b128 v[210:213], v153 offset:20480
	ds_read_b128 v[214:217], v153 offset:21504
	ds_read_b128 v[218:221], v153 offset:22528
	ds_read_b128 v[222:225], v153 offset:23552
	global_load_lds_dwordx4 v[178:179], off
	s_add_i32 m0, s34, 0x2000
	s_add_u32 s60, s6, 0x40000
	v_lshl_add_u64 v[200:201], s[6:7], 0, v[128:129]
	s_addc_u32 s61, s7, 0
	s_add_i32 s34, s35, s17
	global_load_lds_dwordx4 v[200:201], off
	v_lshl_add_u64 v[226:227], s[60:61], 0, v[132:133]
	s_mov_b32 m0, s34
	v_lshl_add_u64 v[228:229], s[42:43], 0, v[130:131]
	global_load_lds_dwordx4 v[226:227], off
	v_lshl_add_u64 v[226:227], s[60:61], 0, v[128:129]
	s_add_i32 m0, s34, 0x2000
	s_nop 0
	global_load_lds_dwordx4 v[226:227], off
	v_lshl_add_u64 v[226:227], s[42:43], 0, v[134:135]
	s_mov_b32 m0, s18
	s_nop 0
	global_load_lds_dwordx4 v[226:227], off
	s_mov_b32 m0, s19
	s_nop 0
	global_load_lds_dwordx4 v[228:229], off
	s_setprio 0
	s_waitcnt vmcnt(8)
	s_waitcnt lgkmcnt(0)
	s_barrier
; #define PG8_STAGE(bufoff, gbase, voff) do { _Pragma("unroll") for (int _i = 0; _i < 2; ++_i) \
;         __builtin_amdgcn_global_load_lds((const unsigned*)((const char*)(gbase) + (voff)[_i]), (PG8_LAS unsigned*)(lds + (bufoff) + ldsw + _i * 8192), 16, 0, 0); } while (0)
; #define PG8_LDA(dst, b, h) do { _Pragma("unroll") for (int m = 0; m < 4; ++m) _Pragma("unroll") for (int k = 0; k < 2; ++k) dst[m][k] = *(const PG8_LAS bf16x8*)(lds + PG8_SA(b, h) + aoff + m * 2048 + k * 1024); } while (0)
; #define PG8_LDB(dst, b, h) do { _Pragma("unroll") for (int n = 0; n < 2; ++n) _Pragma("unroll") for (int k = 0; k < 2; ++k) dst[n][k] = *(const PG8_LAS bf16x8*)(lds + PG8_SB(b, h) + boff + n * 2048 + k * 1024); } while (0)
; #define PG8_MMA(ai, bj, At, Bt) do { __builtin_amdgcn_s_setprio(1); _Pragma("unroll") for (int m = 0; m < 4; ++m) _Pragma("unroll") for (int n = 0; n < 2; ++n) _Pragma("unroll") for (int k = 0; k < 2; ++k) \
;         acc[ai][bj][m][n] = __builtin_amdgcn_mfma_f32_16x16x32_bf16(Bt[n][k], At[m][k], acc[ai][bj][m][n], 0, 0, 0); __builtin_amdgcn_s_setprio(0); } while (0)
; #define PG8_WAIT_V(n) asm volatile("s_waitcnt vmcnt(" #n ")" ::: "memory")
; #define PG8_WAIT_L(n) asm volatile("s_waitcnt lgkmcnt(" #n ")" ::: "memory")
; #define PG8_BAR __builtin_amdgcn_s_barrier()
; #define PG8_SCHED __builtin_amdgcn_sched_barrier(0)
; template <class Epi, class Sched, bool ALIGN_EPI = false, bool SP2 = false>
; __device__ __forceinline__ void gemm_phase(PG8_LAS unsigned char* lds, const Gemm g, const Sched& S, const Epi& E) {
;     ...
;             PG8_WAIT_V(8); PG8_WAIT_L(0); PG8_BAR; PG8_MMA(1, 0, At, B0); PG8_MMA(1, 1, At, B1); PG8_BAR; PG8_SCHED;
;             PG8_LDB(B0, 1, 0); PG8_LDB(B1, 1, 1); PG8_SCHED; PG8_LDA(At, 1, 0); PG8_STAGE(PG8_SA(0, 1), a2 + hstep, voffA);
;             PG8_WAIT_V(8); PG8_WAIT_L(0); PG8_BAR; PG8_MMA(0, 0, At, B0); PG8_MMA(0, 1, At, B1); PG8_BAR; PG8_SCHED;
;             PG8_LDA(At, 1, 1); PG8_STAGE(PG8_SB(1, 0), b3, voffB); PG8_STAGE(PG8_SB(1, 1), b3 + hstep, voffB); PG8_STAGE(PG8_SA(1, 0), a3, voffA);
	s_waitcnt lgkmcnt(0)
	v_mfma_f32_16x16x32_bf16 v[60:63], v[144:147], v[184:187], v[60:63]
	v_mfma_f32_16x16x32_bf16 v[56:59], v[154:157], v[184:187], v[56:59]
	v_mfma_f32_16x16x32_bf16 v[44:47], v[144:147], v[192:195], v[44:47]
	v_mfma_f32_16x16x32_bf16 v[40:43], v[154:157], v[192:195], v[40:43]
	v_mfma_f32_16x16x32_bf16 v[28:31], v[144:147], v[210:213], v[28:31]
	v_mfma_f32_16x16x32_bf16 v[24:27], v[154:157], v[210:213], v[24:27]
	v_mfma_f32_16x16x32_bf16 v[12:15], v[144:147], v[218:221], v[12:15]
	v_mfma_f32_16x16x32_bf16 v[8:11], v[154:157], v[218:221], v[8:11]
	v_mfma_f32_16x16x32_bf16 v[60:63], v[148:151], v[188:191], v[60:63]
	v_mfma_f32_16x16x32_bf16 v[56:59], v[158:161], v[188:191], v[56:59]
	v_mfma_f32_16x16x32_bf16 v[44:47], v[148:151], v[196:199], v[44:47]
	v_mfma_f32_16x16x32_bf16 v[40:43], v[158:161], v[196:199], v[40:43]
	v_mfma_f32_16x16x32_bf16 v[28:31], v[148:151], v[214:217], v[28:31]
	v_mfma_f32_16x16x32_bf16 v[24:27], v[158:161], v[214:217], v[24:27]
	v_mfma_f32_16x16x32_bf16 v[12:15], v[148:151], v[222:225], v[12:15]
	v_mfma_f32_16x16x32_bf16 v[8:11], v[158:161], v[222:225], v[8:11]
	v_mfma_f32_16x16x32_bf16 v[52:55], v[162:165], v[184:187], v[52:55]
	v_mfma_f32_16x16x32_bf16 v[48:51], v[170:173], v[184:187], v[48:51]
	v_mfma_f32_16x16x32_bf16 v[36:39], v[162:165], v[192:195], v[36:39]
	v_mfma_f32_16x16x32_bf16 v[32:35], v[170:173], v[192:195], v[32:35]
	v_mfma_f32_16x16x32_bf16 v[20:23], v[162:165], v[210:213], v[20:23]
	v_mfma_f32_16x16x32_bf16 v[16:19], v[170:173], v[210:213], v[16:19]
	v_mfma_f32_16x16x32_bf16 v[4:7], v[162:165], v[218:221], v[4:7]
	v_mfma_f32_16x16x32_bf16 v[0:3], v[170:173], v[218:221], v[0:3]
	v_mfma_f32_16x16x32_bf16 v[52:55], v[166:169], v[188:191], v[52:55]
	v_mfma_f32_16x16x32_bf16 v[48:51], v[174:177], v[188:191], v[48:51]
	v_mfma_f32_16x16x32_bf16 v[36:39], v[166:169], v[196:199], v[36:39]
	v_mfma_f32_16x16x32_bf16 v[32:35], v[174:177], v[196:199], v[32:35]
	v_mfma_f32_16x16x32_bf16 v[20:23], v[166:169], v[214:217], v[20:23]
	v_mfma_f32_16x16x32_bf16 v[16:19], v[174:177], v[214:217], v[16:19]
	v_mfma_f32_16x16x32_bf16 v[4:7], v[166:169], v[222:225], v[4:7]
	v_mfma_f32_16x16x32_bf16 v[0:3], v[174:177], v[222:225], v[0:3]
	s_barrier
	s_setprio 1
	s_add_i32 s34, 0, 0x18000
	s_add_i32 s35, 0, 0x1c000
	v_add_u32_e32 v158, s34, v152
	v_add_u32_e32 v174, s35, v152
	ds_read_b128 v[144:147], v158
	ds_read_b128 v[148:151], v158 offset:1024
	ds_read_b128 v[154:157], v158 offset:2048
	ds_read_b128 v[158:161], v158 offset:3072
	ds_read_b128 v[162:165], v174
	ds_read_b128 v[166:169], v174 offset:1024
	ds_read_b128 v[170:173], v174 offset:2048
	ds_read_b128 v[174:177], v174 offset:3072
	s_add_u32 s42, s42, 0x40000
	s_addc_u32 s43, s43, 0
	s_mov_b32 m0, s20
	v_lshl_add_u64 v[230:231], s[42:43], 0, v[134:135]
	ds_read_b128 v[184:187], v153 offset:32768
	ds_read_b128 v[188:191], v153 offset:33792
	ds_read_b128 v[192:195], v153 offset:34816
	ds_read_b128 v[196:199], v153 offset:35840
	ds_read_b128 v[210:213], v153 offset:36864
	ds_read_b128 v[214:217], v153 offset:37888
	ds_read_b128 v[218:221], v153 offset:38912
	ds_read_b128 v[222:225], v153 offset:39936
	global_load_lds_dwordx4 v[230:231], off
	v_lshl_add_u64 v[230:231], s[42:43], 0, v[130:131]
	s_mov_b32 m0, s21
	s_nop 0
	global_load_lds_dwordx4 v[230:231], off
	s_setprio 0
	s_waitcnt vmcnt(8)
	s_waitcnt lgkmcnt(0)
	s_barrier
	s_waitcnt lgkmcnt(0)
	v_mfma_f32_16x16x32_bf16 v[124:127], v[144:147], v[184:187], v[124:127]
	v_mfma_f32_16x16x32_bf16 v[120:123], v[154:157], v[184:187], v[120:123]
	v_mfma_f32_16x16x32_bf16 v[108:111], v[144:147], v[192:195], v[108:111]
	v_mfma_f32_16x16x32_bf16 v[104:107], v[154:157], v[192:195], v[104:107]
	v_mfma_f32_16x16x32_bf16 v[92:95], v[144:147], v[210:213], v[92:95]
	v_mfma_f32_16x16x32_bf16 v[88:91], v[154:157], v[210:213], v[88:91]
	v_mfma_f32_16x16x32_bf16 v[76:79], v[144:147], v[218:221], v[76:79]
	v_mfma_f32_16x16x32_bf16 v[72:75], v[154:157], v[218:221], v[72:75]
	v_mfma_f32_16x16x32_bf16 v[124:127], v[148:151], v[188:191], v[124:127]
	v_mfma_f32_16x16x32_bf16 v[120:123], v[158:161], v[188:191], v[120:123]
	v_mfma_f32_16x16x32_bf16 v[108:111], v[148:151], v[196:199], v[108:111]
	v_mfma_f32_16x16x32_bf16 v[104:107], v[158:161], v[196:199], v[104:107]
	v_mfma_f32_16x16x32_bf16 v[92:95], v[148:151], v[214:217], v[92:95]
	v_mfma_f32_16x16x32_bf16 v[88:91], v[158:161], v[214:217], v[88:91]
	v_mfma_f32_16x16x32_bf16 v[76:79], v[148:151], v[222:225], v[76:79]
	v_mfma_f32_16x16x32_bf16 v[72:75], v[158:161], v[222:225], v[72:75]
	v_mfma_f32_16x16x32_bf16 v[116:119], v[162:165], v[184:187], v[116:119]
	v_mfma_f32_16x16x32_bf16 v[112:115], v[170:173], v[184:187], v[112:115]
	v_mfma_f32_16x16x32_bf16 v[100:103], v[162:165], v[192:195], v[100:103]
	v_mfma_f32_16x16x32_bf16 v[96:99], v[170:173], v[192:195], v[96:99]
	v_mfma_f32_16x16x32_bf16 v[84:87], v[162:165], v[210:213], v[84:87]
	v_mfma_f32_16x16x32_bf16 v[80:83], v[170:173], v[210:213], v[80:83]
	v_mfma_f32_16x16x32_bf16 v[68:71], v[162:165], v[218:221], v[68:71]
	v_mfma_f32_16x16x32_bf16 v[64:67], v[170:173], v[218:221], v[64:67]
	v_mfma_f32_16x16x32_bf16 v[116:119], v[166:169], v[188:191], v[116:119]
	v_mfma_f32_16x16x32_bf16 v[112:115], v[174:177], v[188:191], v[112:115]
	v_mfma_f32_16x16x32_bf16 v[100:103], v[166:169], v[196:199], v[100:103]
	v_mfma_f32_16x16x32_bf16 v[96:99], v[174:177], v[196:199], v[96:99]
	v_mfma_f32_16x16x32_bf16 v[84:87], v[166:169], v[214:217], v[84:87]
	v_mfma_f32_16x16x32_bf16 v[80:83], v[174:177], v[214:217], v[80:83]
	v_mfma_f32_16x16x32_bf16 v[68:71], v[166:169], v[222:225], v[68:71]
	v_mfma_f32_16x16x32_bf16 v[64:67], v[174:177], v[222:225], v[64:67]
	s_barrier
; #define PG8_STAGE(bufoff, gbase, voff) do { _Pragma("unroll") for (int _i = 0; _i < 2; ++_i) \
;         __builtin_amdgcn_global_load_lds((const unsigned*)((const char*)(gbase) + (voff)[_i]), (PG8_LAS unsigned*)(lds + (bufoff) + ldsw + _i * 8192), 16, 0, 0); } while (0)
; #define PG8_LDA(dst, b, h) do { _Pragma("unroll") for (int m = 0; m < 4; ++m) _Pragma("unroll") for (int k = 0; k < 2; ++k) dst[m][k] = *(const PG8_LAS bf16x8*)(lds + PG8_SA(b, h) + aoff + m * 2048 + k * 1024); } while (0)
; #define PG8_MMA(ai, bj, At, Bt) do { __builtin_amdgcn_s_setprio(1); _Pragma("unroll") for (int m = 0; m < 4; ++m) _Pragma("unroll") for (int n = 0; n < 2; ++n) _Pragma("unroll") for (int k = 0; k < 2; ++k) \
;         acc[ai][bj][m][n] = __builtin_amdgcn_mfma_f32_16x16x32_bf16(Bt[n][k], At[m][k], acc[ai][bj][m][n], 0, 0, 0); __builtin_amdgcn_s_setprio(0); } while (0)
; #define PG8_WAIT_V(n) asm volatile("s_waitcnt vmcnt(" #n ")" ::: "memory")
; #define PG8_WAIT_L(n) asm volatile("s_waitcnt lgkmcnt(" #n ")" ::: "memory")
; #define PG8_BAR __builtin_amdgcn_s_barrier()
; #define PG8_SCHED __builtin_amdgcn_sched_barrier(0)
; template <class Epi, class Sched, bool ALIGN_EPI = false, bool SP2 = false>
; __device__ __forceinline__ void gemm_phase(PG8_LAS unsigned char* lds, const Gemm g, const Sched& S, const Epi& E) {
;     ...
;             PG8_LDA(At, 1, 1); PG8_STAGE(PG8_SB(1, 0), b3, voffB); PG8_STAGE(PG8_SB(1, 1), b3 + hstep, voffB); PG8_STAGE(PG8_SA(1, 0), a3, voffA);
;             PG8_WAIT_V(8); PG8_WAIT_L(0); PG8_BAR; PG8_MMA(1, 0, At, B0); PG8_MMA(1, 1, At, B1); PG8_BAR; PG8_SCHED;
	s_setprio 1
	s_add_i32 s34, s34, s17
	v_lshl_add_u64 v[178:179], v[178:179], 0, s[58:59]
	s_mov_b32 m0, s34
	ds_read_b128 v[184:187], v153 offset:49152
	ds_read_b128 v[188:191], v153 offset:50176
	ds_read_b128 v[192:195], v153 offset:51200
	ds_read_b128 v[196:199], v153 offset:52224
	ds_read_b128 v[210:213], v153 offset:53248
	ds_read_b128 v[214:217], v153 offset:54272
	ds_read_b128 v[218:221], v153 offset:55296
	ds_read_b128 v[222:225], v153 offset:56320
	global_load_lds_dwordx4 v[178:179], off
	s_add_i32 m0, s34, 0x2000
	s_add_u32 s6, s6, 0x40080
	v_lshl_add_u64 v[178:179], v[200:201], 0, s[58:59]
	s_addc_u32 s7, s7, 0
	s_add_i32 s34, s35, s17
	global_load_lds_dwordx4 v[178:179], off
	v_lshl_add_u64 v[178:179], s[6:7], 0, v[132:133]
	s_mov_b32 m0, s34
	s_nop 0
	global_load_lds_dwordx4 v[178:179], off
	v_lshl_add_u64 v[178:179], s[6:7], 0, v[128:129]
	s_add_i32 m0, s34, 0x2000
	s_nop 0
	global_load_lds_dwordx4 v[178:179], off
	v_lshl_add_u64 v[178:179], v[226:227], 0, s[58:59]
	s_mov_b32 m0, s24
	s_nop 0
	global_load_lds_dwordx4 v[178:179], off
	v_lshl_add_u64 v[178:179], v[228:229], 0, s[58:59]
	s_mov_b32 m0, s25
	s_nop 0
	global_load_lds_dwordx4 v[178:179], off
	s_setprio 0
	s_waitcnt vmcnt(8)
	s_waitcnt lgkmcnt(0)
	s_barrier
	s_waitcnt lgkmcnt(0)
	v_mfma_f32_16x16x32_bf16 v[60:63], v[144:147], v[184:187], v[60:63]
	v_mfma_f32_16x16x32_bf16 v[56:59], v[154:157], v[184:187], v[56:59]
	v_mfma_f32_16x16x32_bf16 v[44:47], v[144:147], v[192:195], v[44:47]
	v_mfma_f32_16x16x32_bf16 v[40:43], v[154:157], v[192:195], v[40:43]
	v_mfma_f32_16x16x32_bf16 v[28:31], v[144:147], v[210:213], v[28:31]
	v_mfma_f32_16x16x32_bf16 v[24:27], v[154:157], v[210:213], v[24:27]
	v_mfma_f32_16x16x32_bf16 v[12:15], v[144:147], v[218:221], v[12:15]
	v_mfma_f32_16x16x32_bf16 v[8:11], v[154:157], v[218:221], v[8:11]
	v_mfma_f32_16x16x32_bf16 v[60:63], v[148:151], v[188:191], v[60:63]
	v_mfma_f32_16x16x32_bf16 v[56:59], v[158:161], v[188:191], v[56:59]
	v_mfma_f32_16x16x32_bf16 v[44:47], v[148:151], v[196:199], v[44:47]
	v_mfma_f32_16x16x32_bf16 v[40:43], v[158:161], v[196:199], v[40:43]
	v_mfma_f32_16x16x32_bf16 v[28:31], v[148:151], v[214:217], v[28:31]
	v_mfma_f32_16x16x32_bf16 v[24:27], v[158:161], v[214:217], v[24:27]
	v_mfma_f32_16x16x32_bf16 v[12:15], v[148:151], v[222:225], v[12:15]
	v_mfma_f32_16x16x32_bf16 v[8:11], v[158:161], v[222:225], v[8:11]
	v_mfma_f32_16x16x32_bf16 v[52:55], v[162:165], v[184:187], v[52:55]
	v_mfma_f32_16x16x32_bf16 v[48:51], v[170:173], v[184:187], v[48:51]
	v_mfma_f32_16x16x32_bf16 v[36:39], v[162:165], v[192:195], v[36:39]
	v_mfma_f32_16x16x32_bf16 v[32:35], v[170:173], v[192:195], v[32:35]
	v_mfma_f32_16x16x32_bf16 v[20:23], v[162:165], v[210:213], v[20:23]
	v_mfma_f32_16x16x32_bf16 v[16:19], v[170:173], v[210:213], v[16:19]
	v_mfma_f32_16x16x32_bf16 v[4:7], v[162:165], v[218:221], v[4:7]
	v_mfma_f32_16x16x32_bf16 v[0:3], v[170:173], v[218:221], v[0:3]
	v_mfma_f32_16x16x32_bf16 v[52:55], v[166:169], v[188:191], v[52:55]
	v_mfma_f32_16x16x32_bf16 v[48:51], v[174:177], v[188:191], v[48:51]
	v_mfma_f32_16x16x32_bf16 v[36:39], v[166:169], v[196:199], v[36:39]
	v_mfma_f32_16x16x32_bf16 v[32:35], v[174:177], v[196:199], v[32:35]
	v_mfma_f32_16x16x32_bf16 v[20:23], v[166:169], v[214:217], v[20:23]
	v_mfma_f32_16x16x32_bf16 v[16:19], v[174:177], v[214:217], v[16:19]
	v_mfma_f32_16x16x32_bf16 v[4:7], v[166:169], v[222:225], v[4:7]
	v_mfma_f32_16x16x32_bf16 v[0:3], v[174:177], v[222:225], v[0:3]
	s_barrier
	s_setprio 1
	s_add_i32 s49, s49, 2
	s_add_u32 s4, s4, 0x100
	s_addc_u32 s5, s5, 0
	s_add_u32 s45, s45, 0x100
	s_addc_u32 s47, s47, 0
	s_cmp_gt_u32 s49, 13
	s_cbranch_scc0 .LBB0_180
	s_and_b64 vcc, exec, s[28:29]
	s_cbranch_vccz .LBB0_183
	s_barrier

; #define PG8_STAGE(bufoff, gbase, voff) do { _Pragma("unroll") for (int _i = 0; _i < 2; ++_i) \
;         __builtin_amdgcn_global_load_lds((const unsigned*)((const char*)(gbase) + (voff)[_i]), (PG8_LAS unsigned*)(lds + (bufoff) + ldsw + _i * 8192), 16, 0, 0); } while (0)
; #define PG8_LDA(dst, b, h) do { _Pragma("unroll") for (int m = 0; m < 4; ++m) _Pragma("unroll") for (int k = 0; k < 2; ++k) dst[m][k] = *(const PG8_LAS bf16x8*)(lds + PG8_SA(b, h) + aoff + m * 2048 + k * 1024); } while (0)
; #define PG8_LDB(dst, b, h) do { _Pragma("unroll") for (int n = 0; n < 2; ++n) _Pragma("unroll") for (int k = 0; k < 2; ++k) dst[n][k] = *(const PG8_LAS bf16x8*)(lds + PG8_SB(b, h) + boff + n * 2048 + k * 1024); } while (0)
; #define PG8_MMA(ai, bj, At, Bt) do { __builtin_amdgcn_s_setprio(1); _Pragma("unroll") for (int m = 0; m < 4; ++m) _Pragma("unroll") for (int n = 0; n < 2; ++n) _Pragma("unroll") for (int k = 0; k < 2; ++k) \
;         acc[ai][bj][m][n] = __builtin_amdgcn_mfma_f32_16x16x32_bf16(Bt[n][k], At[m][k], acc[ai][bj][m][n], 0, 0, 0); __builtin_amdgcn_s_setprio(0); } while (0)
; #define PG8_WAIT_V(n) asm volatile("s_waitcnt vmcnt(" #n ")" ::: "memory")
; #define PG8_WAIT_L(n) asm volatile("s_waitcnt lgkmcnt(" #n ")" ::: "memory")
; template <class Epi, class Sched, bool ALIGN_EPI = false, bool SP2 = false>
; __device__ __forceinline__ void gemm_phase(PG8_LAS unsigned char* lds, const Gemm g, const Sched& S, const Epi& E) {
;     ...
;             const bool last = (t == nt - 2);
;             const char* a1 = cA + (size_t)(t + 1) * kstep;
;             const char* a2 = last ? nA : cA + (size_t)(t + 2) * kstep; const char* b2 = last ? nB : cB + (size_t)(t + 2) * kstep;
;             const char* a3 = a2 + kstep; const char* b3 = b2 + kstep;
;             if (last && has_next) S.a_ready(nxt);
;             if constexpr (SP2) {
;             PG8_LDB(B0, 0, 0); PG8_LDB(B1, 0, 1); PG8_SCHED; PG8_LDA(At, 0, 0); PG8_STAGE(PG8_SA(1, 1), a1 + hstep, voffA);
;             PG8_WAIT_V(8); PG8_WAIT_L(0); PG8_BAR; PG8_MMA(0, 0, At, B0); PG8_MMA(0, 1, At, B1); PG8_BAR; PG8_SCHED;
;             PG8_LDA(At, 0, 1); PG8_STAGE(PG8_SB(0, 0), b2, voffB); PG8_STAGE(PG8_SB(0, 1), b2 + hstep, voffB); PG8_STAGE(PG8_SA(0, 0), a2, voffA);
;             PG8_WAIT_V(8); PG8_WAIT_L(0); PG8_BAR; PG8_MMA(1, 0, At, B0); PG8_MMA(1, 1, At, B1); PG8_BAR; PG8_SCHED;
.LBB0_481:
	s_add_i32 s61, s46, 2
	s_add_u32 s34, s6, 0x80
	s_addc_u32 s35, s7, 0
	s_add_i32 s64, 0, 0x10000
	s_cmp_eq_u32 s25, s46
	s_cselect_b32 s47, s1, s35
	s_cselect_b32 s46, s0, s34
	v_add_u32_e32 v143, s64, v141
	s_cselect_b32 s63, s45, s60
	s_cselect_b32 s62, s44, s53
	s_add_i32 s34, 0, 0x14000
	ds_read_b128 v[144:147], v143
	ds_read_b128 v[148:151], v143 offset:1024
	ds_read_b128 v[152:155], v143 offset:2048
	ds_read_b128 v[156:159], v143 offset:3072
	v_add_u32_e32 v143, s34, v141
	ds_read_b128 v[160:163], v143
	ds_read_b128 v[164:167], v143 offset:1024
	ds_read_b128 v[168:171], v143 offset:2048
	ds_read_b128 v[172:175], v143 offset:3072
	v_lshl_add_u64 v[200:201], s[6:7], 0, v[136:137]
	s_add_i32 m0, s18, 0xc000
	ds_read_b128 v[176:179], v142
	ds_read_b128 v[184:187], v142 offset:1024
	ds_read_b128 v[188:191], v142 offset:2048
	ds_read_b128 v[192:195], v142 offset:3072
	ds_read_b128 v[196:199], v142 offset:4096
	ds_read_b128 v[210:213], v142 offset:5120
	ds_read_b128 v[214:217], v142 offset:6144
	ds_read_b128 v[218:221], v142 offset:7168
	global_load_lds_dwordx4 v[200:201], off
	v_lshl_add_u64 v[200:201], s[6:7], 0, v[138:139]
	s_add_i32 m0, s18, 0xe000
	s_nop 0
	global_load_lds_dwordx4 v[200:201], off
	s_setprio 0
	s_waitcnt vmcnt(8)
	s_waitcnt lgkmcnt(0)
	s_barrier
	s_waitcnt lgkmcnt(0)
	v_mfma_f32_16x16x32_bf16 v[120:123], v[144:147], v[176:179], v[120:123]
	v_mfma_f32_16x16x32_bf16 v[124:127], v[152:155], v[176:179], v[124:127]
	v_mfma_f32_16x16x32_bf16 v[108:111], v[144:147], v[188:191], v[108:111]
	v_mfma_f32_16x16x32_bf16 v[104:107], v[152:155], v[188:191], v[104:107]
	v_mfma_f32_16x16x32_bf16 v[92:95], v[144:147], v[196:199], v[92:95]
	v_mfma_f32_16x16x32_bf16 v[88:91], v[152:155], v[196:199], v[88:91]
	v_mfma_f32_16x16x32_bf16 v[76:79], v[144:147], v[214:217], v[76:79]
	v_mfma_f32_16x16x32_bf16 v[72:75], v[152:155], v[214:217], v[72:75]
	v_mfma_f32_16x16x32_bf16 v[120:123], v[148:151], v[184:187], v[120:123]
	v_mfma_f32_16x16x32_bf16 v[124:127], v[156:159], v[184:187], v[124:127]
	v_mfma_f32_16x16x32_bf16 v[108:111], v[148:151], v[192:195], v[108:111]
	v_mfma_f32_16x16x32_bf16 v[104:107], v[156:159], v[192:195], v[104:107]
	v_mfma_f32_16x16x32_bf16 v[92:95], v[148:151], v[210:213], v[92:95]
	v_mfma_f32_16x16x32_bf16 v[88:91], v[156:159], v[210:213], v[88:91]
	v_mfma_f32_16x16x32_bf16 v[76:79], v[148:151], v[218:221], v[76:79]
	v_mfma_f32_16x16x32_bf16 v[72:75], v[156:159], v[218:221], v[72:75]
	v_mfma_f32_16x16x32_bf16 v[116:119], v[160:163], v[176:179], v[116:119]
	v_mfma_f32_16x16x32_bf16 v[112:115], v[168:171], v[176:179], v[112:115]
	v_mfma_f32_16x16x32_bf16 v[100:103], v[160:163], v[188:191], v[100:103]
	v_mfma_f32_16x16x32_bf16 v[96:99], v[168:171], v[188:191], v[96:99]
	v_mfma_f32_16x16x32_bf16 v[84:87], v[160:163], v[196:199], v[84:87]
	v_mfma_f32_16x16x32_bf16 v[80:83], v[168:171], v[196:199], v[80:83]
	v_mfma_f32_16x16x32_bf16 v[68:71], v[160:163], v[214:217], v[68:71]
	v_mfma_f32_16x16x32_bf16 v[64:67], v[168:171], v[214:217], v[64:67]
	v_mfma_f32_16x16x32_bf16 v[116:119], v[164:167], v[184:187], v[116:119]
	v_mfma_f32_16x16x32_bf16 v[112:115], v[172:175], v[184:187], v[112:115]
	v_mfma_f32_16x16x32_bf16 v[100:103], v[164:167], v[192:195], v[100:103]
	v_mfma_f32_16x16x32_bf16 v[96:99], v[172:175], v[192:195], v[96:99]
	v_mfma_f32_16x16x32_bf16 v[84:87], v[164:167], v[210:213], v[84:87]
	v_mfma_f32_16x16x32_bf16 v[80:83], v[172:175], v[210:213], v[80:83]
	v_mfma_f32_16x16x32_bf16 v[68:71], v[164:167], v[218:221], v[68:71]
	v_mfma_f32_16x16x32_bf16 v[64:67], v[172:175], v[218:221], v[64:67]
	s_barrier
	s_setprio 1
	s_add_i32 s35, s64, s17
	v_lshl_add_u64 v[200:201], s[62:63], 0, v[132:133]
	s_mov_b32 m0, s35
	ds_read_b128 v[176:179], v142 offset:16384
	ds_read_b128 v[184:187], v142 offset:17408
	ds_read_b128 v[188:191], v142 offset:18432
	ds_read_b128 v[192:195], v142 offset:19456
	ds_read_b128 v[196:199], v142 offset:20480
	ds_read_b128 v[210:213], v142 offset:21504
	ds_read_b128 v[214:217], v142 offset:22528
	ds_read_b128 v[218:221], v142 offset:23552
	global_load_lds_dwordx4 v[200:201], off
	s_add_i32 m0, s35, 0x2000
	v_lshl_add_u64 v[222:223], s[62:63], 0, v[128:129]
	s_add_u32 s62, s62, s4
	s_addc_u32 s63, s63, s5
	s_add_i32 s34, s34, s17
	global_load_lds_dwordx4 v[222:223], off
	v_lshl_add_u64 v[224:225], s[62:63], 0, v[132:133]
	s_mov_b32 m0, s34
	v_lshl_add_u64 v[226:227], s[62:63], 0, v[128:129]
	global_load_lds_dwordx4 v[224:225], off
	s_add_i32 m0, s34, 0x2000
	v_lshl_add_u64 v[228:229], s[46:47], 0, v[134:135]
	global_load_lds_dwordx4 v[226:227], off
	s_mov_b32 m0, s18
	v_lshl_add_u64 v[230:231], s[46:47], 0, v[130:131]
	global_load_lds_dwordx4 v[228:229], off
	s_mov_b32 m0, s19
	s_nop 0
	global_load_lds_dwordx4 v[230:231], off
	s_setprio 0
	s_waitcnt vmcnt(8)
	s_waitcnt lgkmcnt(0)
	s_barrier
; #define PG8_STAGE(bufoff, gbase, voff) do { _Pragma("unroll") for (int _i = 0; _i < 2; ++_i) \
;         __builtin_amdgcn_global_load_lds((const unsigned*)((const char*)(gbase) + (voff)[_i]), (PG8_LAS unsigned*)(lds + (bufoff) + ldsw + _i * 8192), 16, 0, 0); } while (0)
; #define PG8_LDA(dst, b, h) do { _Pragma("unroll") for (int m = 0; m < 4; ++m) _Pragma("unroll") for (int k = 0; k < 2; ++k) dst[m][k] = *(const PG8_LAS bf16x8*)(lds + PG8_SA(b, h) + aoff + m * 2048 + k * 1024); } while (0)
; #define PG8_LDB(dst, b, h) do { _Pragma("unroll") for (int n = 0; n < 2; ++n) _Pragma("unroll") for (int k = 0; k < 2; ++k) dst[n][k] = *(const PG8_LAS bf16x8*)(lds + PG8_SB(b, h) + boff + n * 2048 + k * 1024); } while (0)
; #define PG8_MMA(ai, bj, At, Bt) do { __builtin_amdgcn_s_setprio(1); _Pragma("unroll") for (int m = 0; m < 4; ++m) _Pragma("unroll") for (int n = 0; n < 2; ++n) _Pragma("unroll") for (int k = 0; k < 2; ++k) \
;         acc[ai][bj][m][n] = __builtin_amdgcn_mfma_f32_16x16x32_bf16(Bt[n][k], At[m][k], acc[ai][bj][m][n], 0, 0, 0); __builtin_amdgcn_s_setprio(0); } while (0)
; #define PG8_WAIT_V(n) asm volatile("s_waitcnt vmcnt(" #n ")" ::: "memory")
; #define PG8_WAIT_L(n) asm volatile("s_waitcnt lgkmcnt(" #n ")" ::: "memory")
; #define PG8_BAR __builtin_amdgcn_s_barrier()
; #define PG8_SCHED __builtin_amdgcn_sched_barrier(0)
; template <class Epi, class Sched, bool ALIGN_EPI = false, bool SP2 = false>
; __device__ __forceinline__ void gemm_phase(PG8_LAS unsigned char* lds, const Gemm g, const Sched& S, const Epi& E) {
;     ...
;             PG8_WAIT_V(8); PG8_WAIT_L(0); PG8_BAR; PG8_MMA(1, 0, At, B0); PG8_MMA(1, 1, At, B1); PG8_BAR; PG8_SCHED;
;             PG8_LDB(B0, 1, 0); PG8_LDB(B1, 1, 1); PG8_SCHED; PG8_LDA(At, 1, 0); PG8_STAGE(PG8_SA(0, 1), a2 + hstep, voffA);
;             PG8_WAIT_V(8); PG8_WAIT_L(0); PG8_BAR; PG8_MMA(0, 0, At, B0); PG8_MMA(0, 1, At, B1); PG8_BAR; PG8_SCHED;
;             PG8_LDA(At, 1, 1); PG8_STAGE(PG8_SB(1, 0), b3, voffB); PG8_STAGE(PG8_SB(1, 1), b3 + hstep, voffB); PG8_STAGE(PG8_SA(1, 0), a3, voffA);
;             PG8_WAIT_V(8); PG8_WAIT_L(0); PG8_BAR; PG8_MMA(1, 0, At, B0); PG8_MMA(1, 1, At, B1); PG8_BAR; PG8_SCHED;
	s_waitcnt lgkmcnt(0)
	v_mfma_f32_16x16x32_bf16 v[60:63], v[144:147], v[176:179], v[60:63]
	v_mfma_f32_16x16x32_bf16 v[56:59], v[152:155], v[176:179], v[56:59]
	v_mfma_f32_16x16x32_bf16 v[44:47], v[144:147], v[188:191], v[44:47]
	v_mfma_f32_16x16x32_bf16 v[40:43], v[152:155], v[188:191], v[40:43]
	v_mfma_f32_16x16x32_bf16 v[28:31], v[144:147], v[196:199], v[28:31]
	v_mfma_f32_16x16x32_bf16 v[24:27], v[152:155], v[196:199], v[24:27]
	v_mfma_f32_16x16x32_bf16 v[12:15], v[144:147], v[214:217], v[12:15]
	v_mfma_f32_16x16x32_bf16 v[8:11], v[152:155], v[214:217], v[8:11]
	v_mfma_f32_16x16x32_bf16 v[60:63], v[148:151], v[184:187], v[60:63]
	v_mfma_f32_16x16x32_bf16 v[56:59], v[156:159], v[184:187], v[56:59]
	v_mfma_f32_16x16x32_bf16 v[44:47], v[148:151], v[192:195], v[44:47]
	v_mfma_f32_16x16x32_bf16 v[40:43], v[156:159], v[192:195], v[40:43]
	v_mfma_f32_16x16x32_bf16 v[28:31], v[148:151], v[210:213], v[28:31]
	v_mfma_f32_16x16x32_bf16 v[24:27], v[156:159], v[210:213], v[24:27]
	v_mfma_f32_16x16x32_bf16 v[12:15], v[148:151], v[218:221], v[12:15]
	v_mfma_f32_16x16x32_bf16 v[8:11], v[156:159], v[218:221], v[8:11]
	v_mfma_f32_16x16x32_bf16 v[52:55], v[160:163], v[176:179], v[52:55]
	v_mfma_f32_16x16x32_bf16 v[48:51], v[168:171], v[176:179], v[48:51]
	v_mfma_f32_16x16x32_bf16 v[36:39], v[160:163], v[188:191], v[36:39]
	v_mfma_f32_16x16x32_bf16 v[32:35], v[168:171], v[188:191], v[32:35]
	v_mfma_f32_16x16x32_bf16 v[20:23], v[160:163], v[196:199], v[20:23]
	v_mfma_f32_16x16x32_bf16 v[16:19], v[168:171], v[196:199], v[16:19]
	v_mfma_f32_16x16x32_bf16 v[4:7], v[160:163], v[214:217], v[4:7]
	v_mfma_f32_16x16x32_bf16 v[0:3], v[168:171], v[214:217], v[0:3]
	v_mfma_f32_16x16x32_bf16 v[52:55], v[164:167], v[184:187], v[52:55]
	v_mfma_f32_16x16x32_bf16 v[48:51], v[172:175], v[184:187], v[48:51]
	v_mfma_f32_16x16x32_bf16 v[36:39], v[164:167], v[192:195], v[36:39]
	v_mfma_f32_16x16x32_bf16 v[32:35], v[172:175], v[192:195], v[32:35]
	v_mfma_f32_16x16x32_bf16 v[20:23], v[164:167], v[210:213], v[20:23]
	v_mfma_f32_16x16x32_bf16 v[16:19], v[172:175], v[210:213], v[16:19]
	v_mfma_f32_16x16x32_bf16 v[4:7], v[164:167], v[218:221], v[4:7]
	v_mfma_f32_16x16x32_bf16 v[0:3], v[172:175], v[218:221], v[0:3]
	s_barrier
	s_setprio 1
	s_add_i32 s34, 0, 0x18000
	v_add_u32_e32 v143, s34, v141
	s_add_i32 s35, 0, 0x1c000
	ds_read_b128 v[144:147], v143
	ds_read_b128 v[148:151], v143 offset:1024
	ds_read_b128 v[152:155], v143 offset:2048
	ds_read_b128 v[156:159], v143 offset:3072
	v_add_u32_e32 v143, s35, v141
	ds_read_b128 v[160:163], v143
	ds_read_b128 v[164:167], v143 offset:1024
	ds_read_b128 v[168:171], v143 offset:2048
	ds_read_b128 v[172:175], v143 offset:3072
	s_add_u32 s46, s46, s4
	s_addc_u32 s47, s47, s5
	s_mov_b32 m0, s20
	v_lshl_add_u64 v[232:233], s[46:47], 0, v[134:135]
	ds_read_b128 v[176:179], v142 offset:32768
	ds_read_b128 v[184:187], v142 offset:33792
	ds_read_b128 v[188:191], v142 offset:34816
	ds_read_b128 v[192:195], v142 offset:35840
	ds_read_b128 v[196:199], v142 offset:36864
	ds_read_b128 v[210:213], v142 offset:37888
	ds_read_b128 v[214:217], v142 offset:38912
	ds_read_b128 v[218:221], v142 offset:39936
	global_load_lds_dwordx4 v[232:233], off
	v_lshl_add_u64 v[232:233], s[46:47], 0, v[130:131]
	s_mov_b32 m0, s21
	s_nop 0
	global_load_lds_dwordx4 v[232:233], off
	s_setprio 0
	s_waitcnt vmcnt(8)
	s_waitcnt lgkmcnt(0)
	s_barrier
	s_waitcnt lgkmcnt(0)
	v_mfma_f32_16x16x32_bf16 v[120:123], v[144:147], v[176:179], v[120:123]
	v_mfma_f32_16x16x32_bf16 v[124:127], v[152:155], v[176:179], v[124:127]
	v_mfma_f32_16x16x32_bf16 v[108:111], v[144:147], v[188:191], v[108:111]
	v_mfma_f32_16x16x32_bf16 v[104:107], v[152:155], v[188:191], v[104:107]
	v_mfma_f32_16x16x32_bf16 v[92:95], v[144:147], v[196:199], v[92:95]
	v_mfma_f32_16x16x32_bf16 v[88:91], v[152:155], v[196:199], v[88:91]
	v_mfma_f32_16x16x32_bf16 v[76:79], v[144:147], v[214:217], v[76:79]
	v_mfma_f32_16x16x32_bf16 v[72:75], v[152:155], v[214:217], v[72:75]
	v_mfma_f32_16x16x32_bf16 v[120:123], v[148:151], v[184:187], v[120:123]
	v_mfma_f32_16x16x32_bf16 v[124:127], v[156:159], v[184:187], v[124:127]
	v_mfma_f32_16x16x32_bf16 v[108:111], v[148:151], v[192:195], v[108:111]
	v_mfma_f32_16x16x32_bf16 v[104:107], v[156:159], v[192:195], v[104:107]
	v_mfma_f32_16x16x32_bf16 v[92:95], v[148:151], v[210:213], v[92:95]
	v_mfma_f32_16x16x32_bf16 v[88:91], v[156:159], v[210:213], v[88:91]
	v_mfma_f32_16x16x32_bf16 v[76:79], v[148:151], v[218:221], v[76:79]
	v_mfma_f32_16x16x32_bf16 v[72:75], v[156:159], v[218:221], v[72:75]
	v_mfma_f32_16x16x32_bf16 v[116:119], v[160:163], v[176:179], v[116:119]
	v_mfma_f32_16x16x32_bf16 v[112:115], v[168:171], v[176:179], v[112:115]
	v_mfma_f32_16x16x32_bf16 v[100:103], v[160:163], v[188:191], v[100:103]
	v_mfma_f32_16x16x32_bf16 v[96:99], v[168:171], v[188:191], v[96:99]
	v_mfma_f32_16x16x32_bf16 v[84:87], v[160:163], v[196:199], v[84:87]
	v_mfma_f32_16x16x32_bf16 v[80:83], v[168:171], v[196:199], v[80:83]
	v_mfma_f32_16x16x32_bf16 v[68:71], v[160:163], v[214:217], v[68:71]
	v_mfma_f32_16x16x32_bf16 v[64:67], v[168:171], v[214:217], v[64:67]
	v_mfma_f32_16x16x32_bf16 v[116:119], v[164:167], v[184:187], v[116:119]
	v_mfma_f32_16x16x32_bf16 v[112:115], v[172:175], v[184:187], v[112:115]
	v_mfma_f32_16x16x32_bf16 v[100:103], v[164:167], v[192:195], v[100:103]
	v_mfma_f32_16x16x32_bf16 v[96:99], v[172:175], v[192:195], v[96:99]
	v_mfma_f32_16x16x32_bf16 v[84:87], v[164:167], v[210:213], v[84:87]
	v_mfma_f32_16x16x32_bf16 v[80:83], v[172:175], v[210:213], v[80:83]
	v_mfma_f32_16x16x32_bf16 v[68:71], v[164:167], v[218:221], v[68:71]
	v_mfma_f32_16x16x32_bf16 v[64:67], v[172:175], v[218:221], v[64:67]
	s_barrier
; #define PG8_STAGE(bufoff, gbase, voff) do { _Pragma("unroll") for (int _i = 0; _i < 2; ++_i) \
;         __builtin_amdgcn_global_load_lds((const unsigned*)((const char*)(gbase) + (voff)[_i]), (PG8_LAS unsigned*)(lds + (bufoff) + ldsw + _i * 8192), 16, 0, 0); } while (0)
; #define PG8_LDA(dst, b, h) do { _Pragma("unroll") for (int m = 0; m < 4; ++m) _Pragma("unroll") for (int k = 0; k < 2; ++k) dst[m][k] = *(const PG8_LAS bf16x8*)(lds + PG8_SA(b, h) + aoff + m * 2048 + k * 1024); } while (0)
; #define PG8_MMA(ai, bj, At, Bt) do { __builtin_amdgcn_s_setprio(1); _Pragma("unroll") for (int m = 0; m < 4; ++m) _Pragma("unroll") for (int n = 0; n < 2; ++n) _Pragma("unroll") for (int k = 0; k < 2; ++k) \
;         acc[ai][bj][m][n] = __builtin_amdgcn_mfma_f32_16x16x32_bf16(Bt[n][k], At[m][k], acc[ai][bj][m][n], 0, 0, 0); __builtin_amdgcn_s_setprio(0); } while (0)
; #define PG8_WAIT_V(n) asm volatile("s_waitcnt vmcnt(" #n ")" ::: "memory")
; #define PG8_WAIT_L(n) asm volatile("s_waitcnt lgkmcnt(" #n ")" ::: "memory")
; #define PG8_BAR __builtin_amdgcn_s_barrier()
; #define PG8_SCHED __builtin_amdgcn_sched_barrier(0)
; template <class Epi, class Sched, bool ALIGN_EPI = false, bool SP2 = false>
; __device__ __forceinline__ void gemm_phase(PG8_LAS unsigned char* lds, const Gemm g, const Sched& S, const Epi& E) {
;     ...
;         for (int t = 0; t < nt; t += 2) {
;     ...
;             PG8_LDA(At, 1, 1); PG8_STAGE(PG8_SB(1, 0), b3, voffB); PG8_STAGE(PG8_SB(1, 1), b3 + hstep, voffB); PG8_STAGE(PG8_SA(1, 0), a3, voffA);
;             PG8_WAIT_V(8); PG8_WAIT_L(0); PG8_BAR; PG8_MMA(1, 0, At, B0); PG8_MMA(1, 1, At, B1); PG8_BAR; PG8_SCHED;
	s_setprio 1
	s_add_i32 s34, s34, s17
	v_lshl_add_u64 v[200:201], v[200:201], 0, s[58:59]
	s_mov_b32 m0, s34
	ds_read_b128 v[176:179], v142 offset:49152
	ds_read_b128 v[184:187], v142 offset:50176
	ds_read_b128 v[188:191], v142 offset:51200
	ds_read_b128 v[192:195], v142 offset:52224
	ds_read_b128 v[196:199], v142 offset:53248
	ds_read_b128 v[210:213], v142 offset:54272
	ds_read_b128 v[214:217], v142 offset:55296
	ds_read_b128 v[218:221], v142 offset:56320
	global_load_lds_dwordx4 v[200:201], off
	v_lshl_add_u64 v[200:201], v[222:223], 0, s[58:59]
	s_add_i32 m0, s34, 0x2000
	s_add_i32 s34, s35, s17
	global_load_lds_dwordx4 v[200:201], off
	v_lshl_add_u64 v[200:201], v[224:225], 0, s[58:59]
	s_mov_b32 m0, s34
	s_nop 0
	global_load_lds_dwordx4 v[200:201], off
	v_lshl_add_u64 v[200:201], v[226:227], 0, s[58:59]
	s_add_i32 m0, s34, 0x2000
	s_nop 0
	global_load_lds_dwordx4 v[200:201], off
	v_lshl_add_u64 v[200:201], v[228:229], 0, s[58:59]
	s_mov_b32 m0, s22
	s_nop 0
	global_load_lds_dwordx4 v[200:201], off
	v_lshl_add_u64 v[200:201], v[230:231], 0, s[58:59]
	s_mov_b32 m0, s23
	s_nop 0
	global_load_lds_dwordx4 v[200:201], off
	s_setprio 0
	s_waitcnt vmcnt(8)
	s_waitcnt lgkmcnt(0)
	s_barrier
	s_waitcnt lgkmcnt(0)
	v_mfma_f32_16x16x32_bf16 v[60:63], v[144:147], v[176:179], v[60:63]
	v_mfma_f32_16x16x32_bf16 v[56:59], v[152:155], v[176:179], v[56:59]
	v_mfma_f32_16x16x32_bf16 v[44:47], v[144:147], v[188:191], v[44:47]
	v_mfma_f32_16x16x32_bf16 v[40:43], v[152:155], v[188:191], v[40:43]
	v_mfma_f32_16x16x32_bf16 v[28:31], v[144:147], v[196:199], v[28:31]
	v_mfma_f32_16x16x32_bf16 v[24:27], v[152:155], v[196:199], v[24:27]
	v_mfma_f32_16x16x32_bf16 v[12:15], v[144:147], v[214:217], v[12:15]
	v_mfma_f32_16x16x32_bf16 v[8:11], v[152:155], v[214:217], v[8:11]
	v_mfma_f32_16x16x32_bf16 v[60:63], v[148:151], v[184:187], v[60:63]
	v_mfma_f32_16x16x32_bf16 v[56:59], v[156:159], v[184:187], v[56:59]
	v_mfma_f32_16x16x32_bf16 v[44:47], v[148:151], v[192:195], v[44:47]
	v_mfma_f32_16x16x32_bf16 v[40:43], v[156:159], v[192:195], v[40:43]
	v_mfma_f32_16x16x32_bf16 v[28:31], v[148:151], v[210:213], v[28:31]
	v_mfma_f32_16x16x32_bf16 v[24:27], v[156:159], v[210:213], v[24:27]
	v_mfma_f32_16x16x32_bf16 v[12:15], v[148:151], v[218:221], v[12:15]
	v_mfma_f32_16x16x32_bf16 v[8:11], v[156:159], v[218:221], v[8:11]
	v_mfma_f32_16x16x32_bf16 v[52:55], v[160:163], v[176:179], v[52:55]
	v_mfma_f32_16x16x32_bf16 v[48:51], v[168:171], v[176:179], v[48:51]
	v_mfma_f32_16x16x32_bf16 v[36:39], v[160:163], v[188:191], v[36:39]
	v_mfma_f32_16x16x32_bf16 v[32:35], v[168:171], v[188:191], v[32:35]
	v_mfma_f32_16x16x32_bf16 v[20:23], v[160:163], v[196:199], v[20:23]
	v_mfma_f32_16x16x32_bf16 v[16:19], v[168:171], v[196:199], v[16:19]
	v_mfma_f32_16x16x32_bf16 v[4:7], v[160:163], v[214:217], v[4:7]
	v_mfma_f32_16x16x32_bf16 v[0:3], v[168:171], v[214:217], v[0:3]
	v_mfma_f32_16x16x32_bf16 v[52:55], v[164:167], v[184:187], v[52:55]
	v_mfma_f32_16x16x32_bf16 v[48:51], v[172:175], v[184:187], v[48:51]
	v_mfma_f32_16x16x32_bf16 v[36:39], v[164:167], v[192:195], v[36:39]
	v_mfma_f32_16x16x32_bf16 v[32:35], v[172:175], v[192:195], v[32:35]
	v_mfma_f32_16x16x32_bf16 v[20:23], v[164:167], v[210:213], v[20:23]
	v_mfma_f32_16x16x32_bf16 v[16:19], v[172:175], v[210:213], v[16:19]
	v_mfma_f32_16x16x32_bf16 v[4:7], v[164:167], v[218:221], v[4:7]
	v_mfma_f32_16x16x32_bf16 v[0:3], v[172:175], v[218:221], v[0:3]
	s_barrier
	s_setprio 1
	s_add_u32 s6, s6, 0x100
	s_addc_u32 s7, s7, 0
	s_add_u32 s53, s53, 0x100
	s_addc_u32 s60, s60, 0
	s_cmp_ge_i32 s61, s24
	s_mov_b32 s46, s61
	s_cbranch_scc0 .LBB0_481
	v_readlane_b32 s62, v252, 34
	v_readlane_b32 s64, v254, 51
	v_readlane_b32 s63, v252, 35
	v_readlane_b32 s65, v254, 52

; #define PG8_STAGE(bufoff, gbase, voff) do { _Pragma("unroll") for (int _i = 0; _i < 2; ++_i) \
;         __builtin_amdgcn_global_load_lds((const unsigned*)((const char*)(gbase) + (voff)[_i]), (PG8_LAS unsigned*)(lds + (bufoff) + ldsw + _i * 8192), 16, 0, 0); } while (0)
; #define PG8_LDA(dst, b, h) do { _Pragma("unroll") for (int m = 0; m < 4; ++m) _Pragma("unroll") for (int k = 0; k < 2; ++k) dst[m][k] = *(const PG8_LAS bf16x8*)(lds + PG8_SA(b, h) + aoff + m * 2048 + k * 1024); } while (0)
; #define PG8_LDB(dst, b, h) do { _Pragma("unroll") for (int n = 0; n < 2; ++n) _Pragma("unroll") for (int k = 0; k < 2; ++k) dst[n][k] = *(const PG8_LAS bf16x8*)(lds + PG8_SB(b, h) + boff + n * 2048 + k * 1024); } while (0)
; #define PG8_MMA(ai, bj, At, Bt) do { __builtin_amdgcn_s_setprio(1); _Pragma("unroll") for (int m = 0; m < 4; ++m) _Pragma("unroll") for (int n = 0; n < 2; ++n) _Pragma("unroll") for (int k = 0; k < 2; ++k) \
;         acc[ai][bj][m][n] = __builtin_amdgcn_mfma_f32_16x16x32_bf16(Bt[n][k], At[m][k], acc[ai][bj][m][n], 0, 0, 0); __builtin_amdgcn_s_setprio(0); } while (0)
; #define PG8_WAIT_V(n) asm volatile("s_waitcnt vmcnt(" #n ")" ::: "memory")
; #define PG8_WAIT_L(n) asm volatile("s_waitcnt lgkmcnt(" #n ")" ::: "memory")
; template <class Epi, class Sched, bool ALIGN_EPI = false, bool SP2 = false>
; __device__ __forceinline__ void gemm_phase(PG8_LAS unsigned char* lds, const Gemm g, const Sched& S, const Epi& E) {
;     ...
;             const bool last = (t == nt - 2);
;             const char* a1 = cA + (size_t)(t + 1) * kstep;
;             const char* a2 = last ? nA : cA + (size_t)(t + 2) * kstep; const char* b2 = last ? nB : cB + (size_t)(t + 2) * kstep;
;             const char* a3 = a2 + kstep; const char* b3 = b2 + kstep;
;             if (last && has_next) S.a_ready(nxt);
;             if constexpr (SP2) {
;             PG8_LDB(B0, 0, 0); PG8_LDB(B1, 0, 1); PG8_SCHED; PG8_LDA(At, 0, 0); PG8_STAGE(PG8_SA(1, 1), a1 + hstep, voffA);
;             PG8_WAIT_V(8); PG8_WAIT_L(0); PG8_BAR; PG8_MMA(0, 0, At, B0); PG8_MMA(0, 1, At, B1); PG8_BAR; PG8_SCHED;
;             PG8_LDA(At, 0, 1); PG8_STAGE(PG8_SB(0, 0), b2, voffB); PG8_STAGE(PG8_SB(0, 1), b2 + hstep, voffB); PG8_STAGE(PG8_SA(0, 0), a2, voffA);
;             PG8_WAIT_V(8); PG8_WAIT_L(0); PG8_BAR; PG8_MMA(1, 0, At, B0); PG8_MMA(1, 1, At, B1); PG8_BAR; PG8_SCHED;
.LBB0_505:
	s_add_i32 s24, s6, 2
	s_add_u32 s26, s4, 0x80
	s_addc_u32 s7, s5, 0
	s_add_i32 s34, 0, 0x10000
	s_cmp_eq_u32 s79, s6
	s_cselect_b32 s7, s73, s7
	s_cselect_b32 s6, s72, s26
	s_cselect_b32 s27, s31, s15
	s_cselect_b32 s26, s30, s13
	s_add_i32 s35, 0, 0x14000
	v_add_u32_e32 v154, s34, v179
	v_add_u32_e32 v170, s35, v179
	ds_read_b128 v[142:145], v154
	ds_read_b128 v[146:149], v154 offset:1024
	ds_read_b128 v[150:153], v154 offset:2048
	ds_read_b128 v[154:157], v154 offset:3072
	ds_read_b128 v[158:161], v170
	ds_read_b128 v[162:165], v170 offset:1024
	ds_read_b128 v[166:169], v170 offset:2048
	ds_read_b128 v[170:173], v170 offset:3072
	v_lshl_add_u64 v[240:241], s[4:5], 0, v[138:139]
	s_add_i32 m0, s75, 0xc000
	ds_read_b128 v[174:177], v201
	ds_read_b128 v[212:215], v201 offset:1024
	ds_read_b128 v[216:219], v201 offset:2048
	ds_read_b128 v[220:223], v201 offset:3072
	ds_read_b128 v[224:227], v201 offset:4096
	ds_read_b128 v[228:231], v201 offset:5120
	ds_read_b128 v[232:235], v201 offset:6144
	ds_read_b128 v[236:239], v201 offset:7168
	global_load_lds_dwordx4 v[240:241], off
	v_lshl_add_u64 v[240:241], s[4:5], 0, v[140:141]
	s_add_i32 m0, s75, 0xe000
	s_nop 0
	global_load_lds_dwordx4 v[240:241], off
	s_setprio 0
	s_waitcnt vmcnt(8)
	s_waitcnt lgkmcnt(0)
	s_barrier
	s_waitcnt lgkmcnt(0)
	v_mfma_f32_16x16x32_bf16 v[116:119], v[142:145], v[174:177], v[116:119]
	v_mfma_f32_16x16x32_bf16 v[112:115], v[150:153], v[174:177], v[112:115]
	v_mfma_f32_16x16x32_bf16 v[108:111], v[142:145], v[216:219], v[108:111]
	v_mfma_f32_16x16x32_bf16 v[104:107], v[150:153], v[216:219], v[104:107]
	v_mfma_f32_16x16x32_bf16 v[92:95], v[142:145], v[224:227], v[92:95]
	v_mfma_f32_16x16x32_bf16 v[88:91], v[150:153], v[224:227], v[88:91]
	v_mfma_f32_16x16x32_bf16 v[76:79], v[142:145], v[232:235], v[76:79]
	v_mfma_f32_16x16x32_bf16 v[72:75], v[150:153], v[232:235], v[72:75]
	v_mfma_f32_16x16x32_bf16 v[116:119], v[146:149], v[212:215], v[116:119]
	v_mfma_f32_16x16x32_bf16 v[112:115], v[154:157], v[212:215], v[112:115]
	v_mfma_f32_16x16x32_bf16 v[108:111], v[146:149], v[220:223], v[108:111]
	v_mfma_f32_16x16x32_bf16 v[104:107], v[154:157], v[220:223], v[104:107]
	v_mfma_f32_16x16x32_bf16 v[92:95], v[146:149], v[228:231], v[92:95]
	v_mfma_f32_16x16x32_bf16 v[88:91], v[154:157], v[228:231], v[88:91]
	v_mfma_f32_16x16x32_bf16 v[76:79], v[146:149], v[236:239], v[76:79]
	v_mfma_f32_16x16x32_bf16 v[72:75], v[154:157], v[236:239], v[72:75]
	v_mfma_f32_16x16x32_bf16 v[124:127], v[158:161], v[174:177], v[124:127]
	v_mfma_f32_16x16x32_bf16 v[120:123], v[166:169], v[174:177], v[120:123]
	v_mfma_f32_16x16x32_bf16 v[100:103], v[158:161], v[216:219], v[100:103]
	v_mfma_f32_16x16x32_bf16 v[96:99], v[166:169], v[216:219], v[96:99]
	v_mfma_f32_16x16x32_bf16 v[84:87], v[158:161], v[224:227], v[84:87]
	v_mfma_f32_16x16x32_bf16 v[80:83], v[166:169], v[224:227], v[80:83]
	v_mfma_f32_16x16x32_bf16 v[68:71], v[158:161], v[232:235], v[68:71]
	v_mfma_f32_16x16x32_bf16 v[64:67], v[166:169], v[232:235], v[64:67]
	v_mfma_f32_16x16x32_bf16 v[124:127], v[162:165], v[212:215], v[124:127]
	v_mfma_f32_16x16x32_bf16 v[120:123], v[170:173], v[212:215], v[120:123]
	v_mfma_f32_16x16x32_bf16 v[100:103], v[162:165], v[220:223], v[100:103]
	v_mfma_f32_16x16x32_bf16 v[96:99], v[170:173], v[220:223], v[96:99]
	v_mfma_f32_16x16x32_bf16 v[84:87], v[162:165], v[228:231], v[84:87]
	v_mfma_f32_16x16x32_bf16 v[80:83], v[170:173], v[228:231], v[80:83]
	v_mfma_f32_16x16x32_bf16 v[68:71], v[162:165], v[236:239], v[68:71]
	v_mfma_f32_16x16x32_bf16 v[64:67], v[170:173], v[236:239], v[64:67]
	s_barrier
	s_setprio 1
	s_add_i32 s34, s34, s19
	v_lshl_add_u64 v[240:241], s[26:27], 0, v[130:131]
	s_mov_b32 m0, s34
	ds_read_b128 v[174:177], v201 offset:16384
	ds_read_b128 v[212:215], v201 offset:17408
	ds_read_b128 v[216:219], v201 offset:18432
	ds_read_b128 v[220:223], v201 offset:19456
	ds_read_b128 v[224:227], v201 offset:20480
	ds_read_b128 v[228:231], v201 offset:21504
	ds_read_b128 v[232:235], v201 offset:22528
	ds_read_b128 v[236:239], v201 offset:23552
	global_load_lds_dwordx4 v[240:241], off
	s_add_i32 m0, s34, 0x2000
	v_lshl_add_u64 v[242:243], s[26:27], 0, v[134:135]
	s_add_u32 s26, s26, s40
	s_addc_u32 s27, s27, 0
	s_add_i32 s34, s35, s19
	global_load_lds_dwordx4 v[242:243], off
	v_lshl_add_u64 v[244:245], s[26:27], 0, v[130:131]
	s_mov_b32 m0, s34
	v_lshl_add_u64 v[246:247], s[26:27], 0, v[134:135]
	global_load_lds_dwordx4 v[244:245], off
	s_add_i32 m0, s34, 0x2000
	v_lshl_add_u64 v[248:249], s[6:7], 0, v[128:129]
	global_load_lds_dwordx4 v[246:247], off
	s_mov_b32 m0, s75
	v_lshl_add_u64 v[250:251], s[6:7], 0, v[132:133]
	global_load_lds_dwordx4 v[248:249], off
	s_mov_b32 m0, s76
	s_nop 0
	global_load_lds_dwordx4 v[250:251], off
	s_setprio 0
	s_waitcnt vmcnt(8)
	s_waitcnt lgkmcnt(0)
	s_barrier
; #define PG8_STAGE(bufoff, gbase, voff) do { _Pragma("unroll") for (int _i = 0; _i < 2; ++_i) \
;         __builtin_amdgcn_global_load_lds((const unsigned*)((const char*)(gbase) + (voff)[_i]), (PG8_LAS unsigned*)(lds + (bufoff) + ldsw + _i * 8192), 16, 0, 0); } while (0)
; #define PG8_LDA(dst, b, h) do { _Pragma("unroll") for (int m = 0; m < 4; ++m) _Pragma("unroll") for (int k = 0; k < 2; ++k) dst[m][k] = *(const PG8_LAS bf16x8*)(lds + PG8_SA(b, h) + aoff + m * 2048 + k * 1024); } while (0)
; #define PG8_LDB(dst, b, h) do { _Pragma("unroll") for (int n = 0; n < 2; ++n) _Pragma("unroll") for (int k = 0; k < 2; ++k) dst[n][k] = *(const PG8_LAS bf16x8*)(lds + PG8_SB(b, h) + boff + n * 2048 + k * 1024); } while (0)
; #define PG8_MMA(ai, bj, At, Bt) do { __builtin_amdgcn_s_setprio(1); _Pragma("unroll") for (int m = 0; m < 4; ++m) _Pragma("unroll") for (int n = 0; n < 2; ++n) _Pragma("unroll") for (int k = 0; k < 2; ++k) \
;         acc[ai][bj][m][n] = __builtin_amdgcn_mfma_f32_16x16x32_bf16(Bt[n][k], At[m][k], acc[ai][bj][m][n], 0, 0, 0); __builtin_amdgcn_s_setprio(0); } while (0)
; #define PG8_WAIT_V(n) asm volatile("s_waitcnt vmcnt(" #n ")" ::: "memory")
; #define PG8_WAIT_L(n) asm volatile("s_waitcnt lgkmcnt(" #n ")" ::: "memory")
; #define PG8_BAR __builtin_amdgcn_s_barrier()
; #define PG8_SCHED __builtin_amdgcn_sched_barrier(0)
; template <class Epi, class Sched, bool ALIGN_EPI = false, bool SP2 = false>
; __device__ __forceinline__ void gemm_phase(PG8_LAS unsigned char* lds, const Gemm g, const Sched& S, const Epi& E) {
;     ...
;             PG8_WAIT_V(8); PG8_WAIT_L(0); PG8_BAR; PG8_MMA(1, 0, At, B0); PG8_MMA(1, 1, At, B1); PG8_BAR; PG8_SCHED;
;             PG8_LDB(B0, 1, 0); PG8_LDB(B1, 1, 1); PG8_SCHED; PG8_LDA(At, 1, 0); PG8_STAGE(PG8_SA(0, 1), a2 + hstep, voffA);
;             PG8_WAIT_V(8); PG8_WAIT_L(0); PG8_BAR; PG8_MMA(0, 0, At, B0); PG8_MMA(0, 1, At, B1); PG8_BAR; PG8_SCHED;
;             PG8_LDA(At, 1, 1); PG8_STAGE(PG8_SB(1, 0), b3, voffB); PG8_STAGE(PG8_SB(1, 1), b3 + hstep, voffB); PG8_STAGE(PG8_SA(1, 0), a3, voffA);
;             PG8_WAIT_V(8); PG8_WAIT_L(0); PG8_BAR; PG8_MMA(1, 0, At, B0); PG8_MMA(1, 1, At, B1); PG8_BAR; PG8_SCHED;
	s_waitcnt lgkmcnt(0)
	v_mfma_f32_16x16x32_bf16 v[60:63], v[142:145], v[174:177], v[60:63]
	v_mfma_f32_16x16x32_bf16 v[56:59], v[150:153], v[174:177], v[56:59]
	v_mfma_f32_16x16x32_bf16 v[44:47], v[142:145], v[216:219], v[44:47]
	v_mfma_f32_16x16x32_bf16 v[40:43], v[150:153], v[216:219], v[40:43]
	v_mfma_f32_16x16x32_bf16 v[28:31], v[142:145], v[224:227], v[28:31]
	v_mfma_f32_16x16x32_bf16 v[24:27], v[150:153], v[224:227], v[24:27]
	v_mfma_f32_16x16x32_bf16 v[12:15], v[142:145], v[232:235], v[12:15]
	v_mfma_f32_16x16x32_bf16 v[8:11], v[150:153], v[232:235], v[8:11]
	v_mfma_f32_16x16x32_bf16 v[60:63], v[146:149], v[212:215], v[60:63]
	v_mfma_f32_16x16x32_bf16 v[56:59], v[154:157], v[212:215], v[56:59]
	v_mfma_f32_16x16x32_bf16 v[44:47], v[146:149], v[220:223], v[44:47]
	v_mfma_f32_16x16x32_bf16 v[40:43], v[154:157], v[220:223], v[40:43]
	v_mfma_f32_16x16x32_bf16 v[28:31], v[146:149], v[228:231], v[28:31]
	v_mfma_f32_16x16x32_bf16 v[24:27], v[154:157], v[228:231], v[24:27]
	v_mfma_f32_16x16x32_bf16 v[12:15], v[146:149], v[236:239], v[12:15]
	v_mfma_f32_16x16x32_bf16 v[8:11], v[154:157], v[236:239], v[8:11]
	v_mfma_f32_16x16x32_bf16 v[52:55], v[158:161], v[174:177], v[52:55]
	v_mfma_f32_16x16x32_bf16 v[48:51], v[166:169], v[174:177], v[48:51]
	v_mfma_f32_16x16x32_bf16 v[36:39], v[158:161], v[216:219], v[36:39]
	v_mfma_f32_16x16x32_bf16 v[32:35], v[166:169], v[216:219], v[32:35]
	v_mfma_f32_16x16x32_bf16 v[20:23], v[158:161], v[224:227], v[20:23]
	v_mfma_f32_16x16x32_bf16 v[16:19], v[166:169], v[224:227], v[16:19]
	v_mfma_f32_16x16x32_bf16 v[4:7], v[158:161], v[232:235], v[4:7]
	v_mfma_f32_16x16x32_bf16 v[0:3], v[166:169], v[232:235], v[0:3]
	v_mfma_f32_16x16x32_bf16 v[52:55], v[162:165], v[212:215], v[52:55]
	v_mfma_f32_16x16x32_bf16 v[48:51], v[170:173], v[212:215], v[48:51]
	v_mfma_f32_16x16x32_bf16 v[36:39], v[162:165], v[220:223], v[36:39]
	v_mfma_f32_16x16x32_bf16 v[32:35], v[170:173], v[220:223], v[32:35]
	v_mfma_f32_16x16x32_bf16 v[20:23], v[162:165], v[228:231], v[20:23]
	v_mfma_f32_16x16x32_bf16 v[16:19], v[170:173], v[228:231], v[16:19]
	v_mfma_f32_16x16x32_bf16 v[4:7], v[162:165], v[236:239], v[4:7]
	v_mfma_f32_16x16x32_bf16 v[0:3], v[170:173], v[236:239], v[0:3]
	s_barrier
	s_setprio 1
	s_add_i32 s26, 0, 0x18000
	s_add_i32 s27, 0, 0x1c000
	v_add_u32_e32 v154, s26, v179
	v_add_u32_e32 v170, s27, v179
	ds_read_b128 v[142:145], v154
	ds_read_b128 v[146:149], v154 offset:1024
	ds_read_b128 v[150:153], v154 offset:2048
	ds_read_b128 v[154:157], v154 offset:3072
	ds_read_b128 v[158:161], v170
	ds_read_b128 v[162:165], v170 offset:1024
	ds_read_b128 v[166:169], v170 offset:2048
	ds_read_b128 v[170:173], v170 offset:3072
	s_add_u32 s6, s6, s40
	s_addc_u32 s7, s7, 0
	s_mov_b32 m0, s77
	v_lshl_add_u64 v[210:211], s[6:7], 0, v[128:129]
	ds_read_b128 v[174:177], v201 offset:32768
	ds_read_b128 v[212:215], v201 offset:33792
	ds_read_b128 v[216:219], v201 offset:34816
	ds_read_b128 v[220:223], v201 offset:35840
	ds_read_b128 v[224:227], v201 offset:36864
	ds_read_b128 v[228:231], v201 offset:37888
	ds_read_b128 v[232:235], v201 offset:38912
	ds_read_b128 v[236:239], v201 offset:39936
	global_load_lds_dwordx4 v[210:211], off
	v_lshl_add_u64 v[210:211], s[6:7], 0, v[132:133]
	s_mov_b32 m0, s78
	s_nop 0
	global_load_lds_dwordx4 v[210:211], off
	s_setprio 0
	s_waitcnt vmcnt(8)
	s_waitcnt lgkmcnt(0)
	s_barrier
	s_waitcnt lgkmcnt(0)
	v_mfma_f32_16x16x32_bf16 v[116:119], v[142:145], v[174:177], v[116:119]
	v_mfma_f32_16x16x32_bf16 v[112:115], v[150:153], v[174:177], v[112:115]
	v_mfma_f32_16x16x32_bf16 v[108:111], v[142:145], v[216:219], v[108:111]
	v_mfma_f32_16x16x32_bf16 v[104:107], v[150:153], v[216:219], v[104:107]
	v_mfma_f32_16x16x32_bf16 v[92:95], v[142:145], v[224:227], v[92:95]
	v_mfma_f32_16x16x32_bf16 v[88:91], v[150:153], v[224:227], v[88:91]
	v_mfma_f32_16x16x32_bf16 v[76:79], v[142:145], v[232:235], v[76:79]
	v_mfma_f32_16x16x32_bf16 v[72:75], v[150:153], v[232:235], v[72:75]
	v_mfma_f32_16x16x32_bf16 v[116:119], v[146:149], v[212:215], v[116:119]
	v_mfma_f32_16x16x32_bf16 v[112:115], v[154:157], v[212:215], v[112:115]
	v_mfma_f32_16x16x32_bf16 v[108:111], v[146:149], v[220:223], v[108:111]
	v_mfma_f32_16x16x32_bf16 v[104:107], v[154:157], v[220:223], v[104:107]
	v_mfma_f32_16x16x32_bf16 v[92:95], v[146:149], v[228:231], v[92:95]
	v_mfma_f32_16x16x32_bf16 v[88:91], v[154:157], v[228:231], v[88:91]
	v_mfma_f32_16x16x32_bf16 v[76:79], v[146:149], v[236:239], v[76:79]
	v_mfma_f32_16x16x32_bf16 v[72:75], v[154:157], v[236:239], v[72:75]
	v_mfma_f32_16x16x32_bf16 v[124:127], v[158:161], v[174:177], v[124:127]
	v_mfma_f32_16x16x32_bf16 v[120:123], v[166:169], v[174:177], v[120:123]
	v_mfma_f32_16x16x32_bf16 v[100:103], v[158:161], v[216:219], v[100:103]
	v_mfma_f32_16x16x32_bf16 v[96:99], v[166:169], v[216:219], v[96:99]
	v_mfma_f32_16x16x32_bf16 v[84:87], v[158:161], v[224:227], v[84:87]
	v_mfma_f32_16x16x32_bf16 v[80:83], v[166:169], v[224:227], v[80:83]
	v_mfma_f32_16x16x32_bf16 v[68:71], v[158:161], v[232:235], v[68:71]
	v_mfma_f32_16x16x32_bf16 v[64:67], v[166:169], v[232:235], v[64:67]
	v_mfma_f32_16x16x32_bf16 v[124:127], v[162:165], v[212:215], v[124:127]
	v_mfma_f32_16x16x32_bf16 v[120:123], v[170:173], v[212:215], v[120:123]
	v_mfma_f32_16x16x32_bf16 v[100:103], v[162:165], v[220:223], v[100:103]
	v_mfma_f32_16x16x32_bf16 v[96:99], v[170:173], v[220:223], v[96:99]
	v_mfma_f32_16x16x32_bf16 v[84:87], v[162:165], v[228:231], v[84:87]
	v_mfma_f32_16x16x32_bf16 v[80:83], v[170:173], v[228:231], v[80:83]
	v_mfma_f32_16x16x32_bf16 v[68:71], v[162:165], v[236:239], v[68:71]
	v_mfma_f32_16x16x32_bf16 v[64:67], v[170:173], v[236:239], v[64:67]
	s_barrier
; #define PG8_STAGE(bufoff, gbase, voff) do { _Pragma("unroll") for (int _i = 0; _i < 2; ++_i) \
;         __builtin_amdgcn_global_load_lds((const unsigned*)((const char*)(gbase) + (voff)[_i]), (PG8_LAS unsigned*)(lds + (bufoff) + ldsw + _i * 8192), 16, 0, 0); } while (0)
; #define PG8_LDA(dst, b, h) do { _Pragma("unroll") for (int m = 0; m < 4; ++m) _Pragma("unroll") for (int k = 0; k < 2; ++k) dst[m][k] = *(const PG8_LAS bf16x8*)(lds + PG8_SA(b, h) + aoff + m * 2048 + k * 1024); } while (0)
; #define PG8_MMA(ai, bj, At, Bt) do { __builtin_amdgcn_s_setprio(1); _Pragma("unroll") for (int m = 0; m < 4; ++m) _Pragma("unroll") for (int n = 0; n < 2; ++n) _Pragma("unroll") for (int k = 0; k < 2; ++k) \
;         acc[ai][bj][m][n] = __builtin_amdgcn_mfma_f32_16x16x32_bf16(Bt[n][k], At[m][k], acc[ai][bj][m][n], 0, 0, 0); __builtin_amdgcn_s_setprio(0); } while (0)
; #define PG8_WAIT_V(n) asm volatile("s_waitcnt vmcnt(" #n ")" ::: "memory")
; #define PG8_WAIT_L(n) asm volatile("s_waitcnt lgkmcnt(" #n ")" ::: "memory")
; #define PG8_BAR __builtin_amdgcn_s_barrier()
; #define PG8_SCHED __builtin_amdgcn_sched_barrier(0)
; template <class Epi, class Sched, bool ALIGN_EPI = false, bool SP2 = false>
; __device__ __forceinline__ void gemm_phase(PG8_LAS unsigned char* lds, const Gemm g, const Sched& S, const Epi& E) {
;     ...
;         for (int t = 0; t < nt; t += 2) {
;     ...
;             PG8_LDA(At, 1, 1); PG8_STAGE(PG8_SB(1, 0), b3, voffB); PG8_STAGE(PG8_SB(1, 1), b3 + hstep, voffB); PG8_STAGE(PG8_SA(1, 0), a3, voffA);
;             PG8_WAIT_V(8); PG8_WAIT_L(0); PG8_BAR; PG8_MMA(1, 0, At, B0); PG8_MMA(1, 1, At, B1); PG8_BAR; PG8_SCHED;
	s_setprio 1
	s_add_i32 s6, s26, s19
	v_lshl_add_u64 v[210:211], v[240:241], 0, s[58:59]
	s_mov_b32 m0, s6
	ds_read_b128 v[174:177], v201 offset:49152
	ds_read_b128 v[212:215], v201 offset:50176
	ds_read_b128 v[216:219], v201 offset:51200
	ds_read_b128 v[220:223], v201 offset:52224
	ds_read_b128 v[224:227], v201 offset:53248
	ds_read_b128 v[228:231], v201 offset:54272
	ds_read_b128 v[232:235], v201 offset:55296
	ds_read_b128 v[236:239], v201 offset:56320
	global_load_lds_dwordx4 v[210:211], off
	v_lshl_add_u64 v[210:211], v[242:243], 0, s[58:59]
	s_add_i32 m0, s6, 0x2000
	s_add_i32 s6, s27, s19
	global_load_lds_dwordx4 v[210:211], off
	v_lshl_add_u64 v[210:211], v[244:245], 0, s[58:59]
	s_mov_b32 m0, s6
	s_nop 0
	global_load_lds_dwordx4 v[210:211], off
	v_lshl_add_u64 v[210:211], v[246:247], 0, s[58:59]
	s_add_i32 m0, s6, 0x2000
	s_nop 0
	global_load_lds_dwordx4 v[210:211], off
	v_lshl_add_u64 v[210:211], v[248:249], 0, s[58:59]
	s_mov_b32 m0, s96
	s_nop 0
	global_load_lds_dwordx4 v[210:211], off
	v_lshl_add_u64 v[210:211], v[250:251], 0, s[58:59]
	s_mov_b32 m0, s97
	s_nop 0
	global_load_lds_dwordx4 v[210:211], off
	s_setprio 0
	s_waitcnt vmcnt(8)
	s_waitcnt lgkmcnt(0)
	s_barrier
	s_waitcnt lgkmcnt(0)
	v_mfma_f32_16x16x32_bf16 v[60:63], v[142:145], v[174:177], v[60:63]
	v_mfma_f32_16x16x32_bf16 v[56:59], v[150:153], v[174:177], v[56:59]
	v_mfma_f32_16x16x32_bf16 v[44:47], v[142:145], v[216:219], v[44:47]
	v_mfma_f32_16x16x32_bf16 v[40:43], v[150:153], v[216:219], v[40:43]
	v_mfma_f32_16x16x32_bf16 v[28:31], v[142:145], v[224:227], v[28:31]
	v_mfma_f32_16x16x32_bf16 v[24:27], v[150:153], v[224:227], v[24:27]
	v_mfma_f32_16x16x32_bf16 v[12:15], v[142:145], v[232:235], v[12:15]
	v_mfma_f32_16x16x32_bf16 v[8:11], v[150:153], v[232:235], v[8:11]
	v_mfma_f32_16x16x32_bf16 v[60:63], v[146:149], v[212:215], v[60:63]
	v_mfma_f32_16x16x32_bf16 v[56:59], v[154:157], v[212:215], v[56:59]
	v_mfma_f32_16x16x32_bf16 v[44:47], v[146:149], v[220:223], v[44:47]
	v_mfma_f32_16x16x32_bf16 v[40:43], v[154:157], v[220:223], v[40:43]
	v_mfma_f32_16x16x32_bf16 v[28:31], v[146:149], v[228:231], v[28:31]
	v_mfma_f32_16x16x32_bf16 v[24:27], v[154:157], v[228:231], v[24:27]
	v_mfma_f32_16x16x32_bf16 v[12:15], v[146:149], v[236:239], v[12:15]
	v_mfma_f32_16x16x32_bf16 v[8:11], v[154:157], v[236:239], v[8:11]
	v_mfma_f32_16x16x32_bf16 v[52:55], v[158:161], v[174:177], v[52:55]
	v_mfma_f32_16x16x32_bf16 v[48:51], v[166:169], v[174:177], v[48:51]
	v_mfma_f32_16x16x32_bf16 v[36:39], v[158:161], v[216:219], v[36:39]
	v_mfma_f32_16x16x32_bf16 v[32:35], v[166:169], v[216:219], v[32:35]
	v_mfma_f32_16x16x32_bf16 v[20:23], v[158:161], v[224:227], v[20:23]
	v_mfma_f32_16x16x32_bf16 v[16:19], v[166:169], v[224:227], v[16:19]
	v_mfma_f32_16x16x32_bf16 v[4:7], v[158:161], v[232:235], v[4:7]
	v_mfma_f32_16x16x32_bf16 v[0:3], v[166:169], v[232:235], v[0:3]
	v_mfma_f32_16x16x32_bf16 v[52:55], v[162:165], v[212:215], v[52:55]
	v_mfma_f32_16x16x32_bf16 v[48:51], v[170:173], v[212:215], v[48:51]
	v_mfma_f32_16x16x32_bf16 v[36:39], v[162:165], v[220:223], v[36:39]
	v_mfma_f32_16x16x32_bf16 v[32:35], v[170:173], v[220:223], v[32:35]
	v_mfma_f32_16x16x32_bf16 v[20:23], v[162:165], v[228:231], v[20:23]
	v_mfma_f32_16x16x32_bf16 v[16:19], v[170:173], v[228:231], v[16:19]
	v_mfma_f32_16x16x32_bf16 v[4:7], v[162:165], v[236:239], v[4:7]
	v_mfma_f32_16x16x32_bf16 v[0:3], v[170:173], v[236:239], v[0:3]
	s_barrier
	s_setprio 1
	s_add_u32 s4, s4, 0x100
	s_addc_u32 s5, s5, 0
	s_add_u32 s13, s13, 0x100
	s_addc_u32 s15, s15, 0
	s_cmp_ge_u32 s24, s74
	s_mov_b32 s6, s24
	s_cbranch_scc0 .LBB0_505
	v_readlane_b32 s4, v255, 4
	v_readlane_b32 s5, v255, 5
	s_and_b64 vcc, exec, s[4:5]
	s_cbranch_vccz .LBB0_508
	s_barrier

; #define PG8_STAGE(bufoff, gbase, voff) do { _Pragma("unroll") for (int _i = 0; _i < 2; ++_i) \
;         __builtin_amdgcn_global_load_lds((const unsigned*)((const char*)(gbase) + (voff)[_i]), (PG8_LAS unsigned*)(lds + (bufoff) + ldsw + _i * 8192), 16, 0, 0); } while (0)
; #define PG8_LDA(dst, b, h) do { _Pragma("unroll") for (int m = 0; m < 4; ++m) _Pragma("unroll") for (int k = 0; k < 2; ++k) dst[m][k] = *(const PG8_LAS bf16x8*)(lds + PG8_SA(b, h) + aoff + m * 2048 + k * 1024); } while (0)
; #define PG8_LDB(dst, b, h) do { _Pragma("unroll") for (int n = 0; n < 2; ++n) _Pragma("unroll") for (int k = 0; k < 2; ++k) dst[n][k] = *(const PG8_LAS bf16x8*)(lds + PG8_SB(b, h) + boff + n * 2048 + k * 1024); } while (0)
; #define PG8_MMA(ai, bj, At, Bt) do { __builtin_amdgcn_s_setprio(1); _Pragma("unroll") for (int m = 0; m < 4; ++m) _Pragma("unroll") for (int n = 0; n < 2; ++n) _Pragma("unroll") for (int k = 0; k < 2; ++k) \
;         acc[ai][bj][m][n] = __builtin_amdgcn_mfma_f32_16x16x32_bf16(Bt[n][k], At[m][k], acc[ai][bj][m][n], 0, 0, 0); __builtin_amdgcn_s_setprio(0); } while (0)
; #define PG8_WAIT_V(n) asm volatile("s_waitcnt vmcnt(" #n ")" ::: "memory")
; #define PG8_WAIT_L(n) asm volatile("s_waitcnt lgkmcnt(" #n ")" ::: "memory")
; template <class Epi, class Sched, bool ALIGN_EPI = false, bool SP2 = false>
; __device__ __forceinline__ void gemm_phase(PG8_LAS unsigned char* lds, const Gemm g, const Sched& S, const Epi& E) {
;     ...
;             const bool last = (t == nt - 2);
;             const char* a1 = cA + (size_t)(t + 1) * kstep;
;             const char* a2 = last ? nA : cA + (size_t)(t + 2) * kstep; const char* b2 = last ? nB : cB + (size_t)(t + 2) * kstep;
;             const char* a3 = a2 + kstep; const char* b3 = b2 + kstep;
;             if (last && has_next) S.a_ready(nxt);
;             if constexpr (SP2) {
;             PG8_LDB(B0, 0, 0); PG8_LDB(B1, 0, 1); PG8_SCHED; PG8_LDA(At, 0, 0); PG8_STAGE(PG8_SA(1, 1), a1 + hstep, voffA);
;             PG8_WAIT_V(8); PG8_WAIT_L(0); PG8_BAR; PG8_MMA(0, 0, At, B0); PG8_MMA(0, 1, At, B1); PG8_BAR; PG8_SCHED;
;             PG8_LDA(At, 0, 1); PG8_STAGE(PG8_SB(0, 0), b2, voffB); PG8_STAGE(PG8_SB(0, 1), b2 + hstep, voffB); PG8_STAGE(PG8_SA(0, 0), a2, voffA);
;             PG8_WAIT_V(8); PG8_WAIT_L(0); PG8_BAR; PG8_MMA(1, 0, At, B0); PG8_MMA(1, 1, At, B1); PG8_BAR; PG8_SCHED;
.LBB0_890:
	s_add_i32 s97, s42, 2
	s_add_u32 s34, s6, 0x80
	s_addc_u32 s35, s7, 0
	s_add_i32 s16, 0, 0x10000
	s_cmp_eq_u32 s13, s42
	s_cselect_b32 s43, s45, s35
	s_cselect_b32 s42, s46, s34
	s_cselect_b32 vcc_hi, s47, s79
	s_cselect_b32 vcc_lo, s49, s50
	s_add_i32 s34, 0, 0x14000
	v_add_u32_e32 v140, s16, v210
	v_add_u32_e32 v156, s34, v210
	ds_read_b128 v[128:131], v140
	ds_read_b128 v[132:135], v140 offset:1024
	ds_read_b128 v[136:139], v140 offset:2048
	ds_read_b128 v[140:143], v140 offset:3072
	ds_read_b128 v[144:147], v156
	ds_read_b128 v[148:151], v156 offset:1024
	ds_read_b128 v[152:155], v156 offset:2048
	ds_read_b128 v[156:159], v156 offset:3072
	v_lshl_add_u64 v[178:179], s[6:7], 0, v[170:171]
	s_add_i32 m0, s19, 0xc000
	ds_read_b128 v[174:177], v215
	ds_read_b128 v[184:187], v215 offset:1024
	ds_read_b128 v[188:191], v215 offset:2048
	ds_read_b128 v[192:195], v215 offset:3072
	ds_read_b128 v[196:199], v215 offset:4096
	ds_read_b128 v[216:219], v215 offset:5120
	ds_read_b128 v[220:223], v215 offset:6144
	ds_read_b128 v[224:227], v215 offset:7168
	global_load_lds_dwordx4 v[178:179], off
	v_lshl_add_u64 v[178:179], s[6:7], 0, v[172:173]
	s_add_i32 m0, s19, 0xe000
	s_nop 0
	global_load_lds_dwordx4 v[178:179], off
	s_setprio 0
	s_waitcnt vmcnt(8)
	s_waitcnt lgkmcnt(0)
	s_barrier
	s_waitcnt lgkmcnt(0)
	v_mfma_f32_16x16x32_bf16 v[124:127], v[128:131], v[174:177], v[124:127]
	v_mfma_f32_16x16x32_bf16 v[120:123], v[136:139], v[174:177], v[120:123]
	v_mfma_f32_16x16x32_bf16 v[108:111], v[128:131], v[188:191], v[108:111]
	v_mfma_f32_16x16x32_bf16 v[104:107], v[136:139], v[188:191], v[104:107]
	v_mfma_f32_16x16x32_bf16 v[92:95], v[128:131], v[196:199], v[92:95]
	v_mfma_f32_16x16x32_bf16 v[88:91], v[136:139], v[196:199], v[88:91]
	v_mfma_f32_16x16x32_bf16 v[76:79], v[128:131], v[220:223], v[76:79]
	v_mfma_f32_16x16x32_bf16 v[72:75], v[136:139], v[220:223], v[72:75]
	v_mfma_f32_16x16x32_bf16 v[124:127], v[132:135], v[184:187], v[124:127]
	v_mfma_f32_16x16x32_bf16 v[120:123], v[140:143], v[184:187], v[120:123]
	v_mfma_f32_16x16x32_bf16 v[108:111], v[132:135], v[192:195], v[108:111]
	v_mfma_f32_16x16x32_bf16 v[104:107], v[140:143], v[192:195], v[104:107]
	v_mfma_f32_16x16x32_bf16 v[92:95], v[132:135], v[216:219], v[92:95]
	v_mfma_f32_16x16x32_bf16 v[88:91], v[140:143], v[216:219], v[88:91]
	v_mfma_f32_16x16x32_bf16 v[76:79], v[132:135], v[224:227], v[76:79]
	v_mfma_f32_16x16x32_bf16 v[72:75], v[140:143], v[224:227], v[72:75]
	v_mfma_f32_16x16x32_bf16 v[116:119], v[144:147], v[174:177], v[116:119]
	v_mfma_f32_16x16x32_bf16 v[112:115], v[152:155], v[174:177], v[112:115]
	v_mfma_f32_16x16x32_bf16 v[100:103], v[144:147], v[188:191], v[100:103]
	v_mfma_f32_16x16x32_bf16 v[96:99], v[152:155], v[188:191], v[96:99]
	v_mfma_f32_16x16x32_bf16 v[84:87], v[144:147], v[196:199], v[84:87]
	v_mfma_f32_16x16x32_bf16 v[80:83], v[152:155], v[196:199], v[80:83]
	v_mfma_f32_16x16x32_bf16 v[68:71], v[144:147], v[220:223], v[68:71]
	v_mfma_f32_16x16x32_bf16 v[64:67], v[152:155], v[220:223], v[64:67]
	v_mfma_f32_16x16x32_bf16 v[116:119], v[148:151], v[184:187], v[116:119]
	v_mfma_f32_16x16x32_bf16 v[112:115], v[156:159], v[184:187], v[112:115]
	v_mfma_f32_16x16x32_bf16 v[100:103], v[148:151], v[192:195], v[100:103]
	v_mfma_f32_16x16x32_bf16 v[96:99], v[156:159], v[192:195], v[96:99]
	v_mfma_f32_16x16x32_bf16 v[84:87], v[148:151], v[216:219], v[84:87]
	v_mfma_f32_16x16x32_bf16 v[80:83], v[156:159], v[216:219], v[80:83]
	v_mfma_f32_16x16x32_bf16 v[68:71], v[148:151], v[224:227], v[68:71]
	v_mfma_f32_16x16x32_bf16 v[64:67], v[156:159], v[224:227], v[64:67]
	s_barrier
	s_setprio 1
	s_add_i32 s16, s16, s24
	v_lshl_add_u64 v[178:179], vcc, 0, v[180:181]
	s_mov_b32 m0, s16
	ds_read_b128 v[174:177], v215 offset:16384
	ds_read_b128 v[184:187], v215 offset:17408
	ds_read_b128 v[188:191], v215 offset:18432
	ds_read_b128 v[192:195], v215 offset:19456
	ds_read_b128 v[196:199], v215 offset:20480
	ds_read_b128 v[216:219], v215 offset:21504
	ds_read_b128 v[220:223], v215 offset:22528
	ds_read_b128 v[224:227], v215 offset:23552
	global_load_lds_dwordx4 v[178:179], off
	s_add_i32 m0, s16, 0x2000
	v_lshl_add_u64 v[200:201], vcc, 0, v[160:161]
	s_add_u32 vcc_lo, vcc_lo, s48
	s_addc_u32 vcc_hi, vcc_hi, 0
	s_add_i32 s16, s34, s24
	global_load_lds_dwordx4 v[200:201], off
	v_lshl_add_u64 v[228:229], vcc, 0, v[180:181]
	s_mov_b32 m0, s16
	v_lshl_add_u64 v[230:231], vcc, 0, v[160:161]
	global_load_lds_dwordx4 v[228:229], off
	s_add_i32 m0, s16, 0x2000
	v_lshl_add_u64 v[232:233], s[42:43], 0, v[164:165]
	global_load_lds_dwordx4 v[230:231], off
	s_mov_b32 m0, s19
	v_lshl_add_u64 v[234:235], s[42:43], 0, v[162:163]
	global_load_lds_dwordx4 v[232:233], off
	s_mov_b32 m0, s85
	s_nop 0
	global_load_lds_dwordx4 v[234:235], off
	s_setprio 0
	s_waitcnt vmcnt(8)
	s_waitcnt lgkmcnt(0)
	s_barrier
; #define PG8_STAGE(bufoff, gbase, voff) do { _Pragma("unroll") for (int _i = 0; _i < 2; ++_i) \
;         __builtin_amdgcn_global_load_lds((const unsigned*)((const char*)(gbase) + (voff)[_i]), (PG8_LAS unsigned*)(lds + (bufoff) + ldsw + _i * 8192), 16, 0, 0); } while (0)
; #define PG8_LDA(dst, b, h) do { _Pragma("unroll") for (int m = 0; m < 4; ++m) _Pragma("unroll") for (int k = 0; k < 2; ++k) dst[m][k] = *(const PG8_LAS bf16x8*)(lds + PG8_SA(b, h) + aoff + m * 2048 + k * 1024); } while (0)
; #define PG8_LDB(dst, b, h) do { _Pragma("unroll") for (int n = 0; n < 2; ++n) _Pragma("unroll") for (int k = 0; k < 2; ++k) dst[n][k] = *(const PG8_LAS bf16x8*)(lds + PG8_SB(b, h) + boff + n * 2048 + k * 1024); } while (0)
; #define PG8_MMA(ai, bj, At, Bt) do { __builtin_amdgcn_s_setprio(1); _Pragma("unroll") for (int m = 0; m < 4; ++m) _Pragma("unroll") for (int n = 0; n < 2; ++n) _Pragma("unroll") for (int k = 0; k < 2; ++k) \
;         acc[ai][bj][m][n] = __builtin_amdgcn_mfma_f32_16x16x32_bf16(Bt[n][k], At[m][k], acc[ai][bj][m][n], 0, 0, 0); __builtin_amdgcn_s_setprio(0); } while (0)
; #define PG8_WAIT_V(n) asm volatile("s_waitcnt vmcnt(" #n ")" ::: "memory")
; #define PG8_WAIT_L(n) asm volatile("s_waitcnt lgkmcnt(" #n ")" ::: "memory")
; #define PG8_BAR __builtin_amdgcn_s_barrier()
; #define PG8_SCHED __builtin_amdgcn_sched_barrier(0)
; template <class Epi, class Sched, bool ALIGN_EPI = false, bool SP2 = false>
; __device__ __forceinline__ void gemm_phase(PG8_LAS unsigned char* lds, const Gemm g, const Sched& S, const Epi& E) {
;     ...
;             PG8_WAIT_V(8); PG8_WAIT_L(0); PG8_BAR; PG8_MMA(1, 0, At, B0); PG8_MMA(1, 1, At, B1); PG8_BAR; PG8_SCHED;
;             PG8_LDB(B0, 1, 0); PG8_LDB(B1, 1, 1); PG8_SCHED; PG8_LDA(At, 1, 0); PG8_STAGE(PG8_SA(0, 1), a2 + hstep, voffA);
;             PG8_WAIT_V(8); PG8_WAIT_L(0); PG8_BAR; PG8_MMA(0, 0, At, B0); PG8_MMA(0, 1, At, B1); PG8_BAR; PG8_SCHED;
;             PG8_LDA(At, 1, 1); PG8_STAGE(PG8_SB(1, 0), b3, voffB); PG8_STAGE(PG8_SB(1, 1), b3 + hstep, voffB); PG8_STAGE(PG8_SA(1, 0), a3, voffA);
;             PG8_WAIT_V(8); PG8_WAIT_L(0); PG8_BAR; PG8_MMA(1, 0, At, B0); PG8_MMA(1, 1, At, B1); PG8_BAR; PG8_SCHED;
	s_waitcnt lgkmcnt(0)
	v_mfma_f32_16x16x32_bf16 v[60:63], v[128:131], v[174:177], v[60:63]
	v_mfma_f32_16x16x32_bf16 v[56:59], v[136:139], v[174:177], v[56:59]
	v_mfma_f32_16x16x32_bf16 v[44:47], v[128:131], v[188:191], v[44:47]
	v_mfma_f32_16x16x32_bf16 v[40:43], v[136:139], v[188:191], v[40:43]
	v_mfma_f32_16x16x32_bf16 v[28:31], v[128:131], v[196:199], v[28:31]
	v_mfma_f32_16x16x32_bf16 v[24:27], v[136:139], v[196:199], v[24:27]
	v_mfma_f32_16x16x32_bf16 v[12:15], v[128:131], v[220:223], v[12:15]
	v_mfma_f32_16x16x32_bf16 v[8:11], v[136:139], v[220:223], v[8:11]
	v_mfma_f32_16x16x32_bf16 v[60:63], v[132:135], v[184:187], v[60:63]
	v_mfma_f32_16x16x32_bf16 v[56:59], v[140:143], v[184:187], v[56:59]
	v_mfma_f32_16x16x32_bf16 v[44:47], v[132:135], v[192:195], v[44:47]
	v_mfma_f32_16x16x32_bf16 v[40:43], v[140:143], v[192:195], v[40:43]
	v_mfma_f32_16x16x32_bf16 v[28:31], v[132:135], v[216:219], v[28:31]
	v_mfma_f32_16x16x32_bf16 v[24:27], v[140:143], v[216:219], v[24:27]
	v_mfma_f32_16x16x32_bf16 v[12:15], v[132:135], v[224:227], v[12:15]
	v_mfma_f32_16x16x32_bf16 v[8:11], v[140:143], v[224:227], v[8:11]
	v_mfma_f32_16x16x32_bf16 v[52:55], v[144:147], v[174:177], v[52:55]
	v_mfma_f32_16x16x32_bf16 v[48:51], v[152:155], v[174:177], v[48:51]
	v_mfma_f32_16x16x32_bf16 v[36:39], v[144:147], v[188:191], v[36:39]
	v_mfma_f32_16x16x32_bf16 v[32:35], v[152:155], v[188:191], v[32:35]
	v_mfma_f32_16x16x32_bf16 v[20:23], v[144:147], v[196:199], v[20:23]
	v_mfma_f32_16x16x32_bf16 v[16:19], v[152:155], v[196:199], v[16:19]
	v_mfma_f32_16x16x32_bf16 v[4:7], v[144:147], v[220:223], v[4:7]
	v_mfma_f32_16x16x32_bf16 v[0:3], v[152:155], v[220:223], v[0:3]
	v_mfma_f32_16x16x32_bf16 v[52:55], v[148:151], v[184:187], v[52:55]
	v_mfma_f32_16x16x32_bf16 v[48:51], v[156:159], v[184:187], v[48:51]
	v_mfma_f32_16x16x32_bf16 v[36:39], v[148:151], v[192:195], v[36:39]
	v_mfma_f32_16x16x32_bf16 v[32:35], v[156:159], v[192:195], v[32:35]
	v_mfma_f32_16x16x32_bf16 v[20:23], v[148:151], v[216:219], v[20:23]
	v_mfma_f32_16x16x32_bf16 v[16:19], v[156:159], v[216:219], v[16:19]
	v_mfma_f32_16x16x32_bf16 v[4:7], v[148:151], v[224:227], v[4:7]
	v_mfma_f32_16x16x32_bf16 v[0:3], v[156:159], v[224:227], v[0:3]
	s_barrier
	s_setprio 1
	s_add_i32 s16, 0, 0x18000
	s_add_i32 s34, 0, 0x1c000
	v_add_u32_e32 v140, s16, v210
	v_add_u32_e32 v156, s34, v210
	ds_read_b128 v[128:131], v140
	ds_read_b128 v[132:135], v140 offset:1024
	ds_read_b128 v[136:139], v140 offset:2048
	ds_read_b128 v[140:143], v140 offset:3072
	ds_read_b128 v[144:147], v156
	ds_read_b128 v[148:151], v156 offset:1024
	ds_read_b128 v[152:155], v156 offset:2048
	ds_read_b128 v[156:159], v156 offset:3072
	s_add_u32 s42, s42, s48
	s_addc_u32 s43, s43, 0
	s_mov_b32 m0, s64
	v_lshl_add_u64 v[236:237], s[42:43], 0, v[164:165]
	ds_read_b128 v[174:177], v215 offset:32768
	ds_read_b128 v[184:187], v215 offset:33792
	ds_read_b128 v[188:191], v215 offset:34816
	ds_read_b128 v[192:195], v215 offset:35840
	ds_read_b128 v[196:199], v215 offset:36864
	ds_read_b128 v[216:219], v215 offset:37888
	ds_read_b128 v[220:223], v215 offset:38912
	ds_read_b128 v[224:227], v215 offset:39936
	global_load_lds_dwordx4 v[236:237], off
	v_lshl_add_u64 v[236:237], s[42:43], 0, v[162:163]
	s_mov_b32 m0, s65
	s_nop 0
	global_load_lds_dwordx4 v[236:237], off
	s_setprio 0
	s_waitcnt vmcnt(8)
	s_waitcnt lgkmcnt(0)
	s_barrier
	s_waitcnt lgkmcnt(0)
	v_mfma_f32_16x16x32_bf16 v[124:127], v[128:131], v[174:177], v[124:127]
	v_mfma_f32_16x16x32_bf16 v[120:123], v[136:139], v[174:177], v[120:123]
	v_mfma_f32_16x16x32_bf16 v[108:111], v[128:131], v[188:191], v[108:111]
	v_mfma_f32_16x16x32_bf16 v[104:107], v[136:139], v[188:191], v[104:107]
	v_mfma_f32_16x16x32_bf16 v[92:95], v[128:131], v[196:199], v[92:95]
	v_mfma_f32_16x16x32_bf16 v[88:91], v[136:139], v[196:199], v[88:91]
	v_mfma_f32_16x16x32_bf16 v[76:79], v[128:131], v[220:223], v[76:79]
	v_mfma_f32_16x16x32_bf16 v[72:75], v[136:139], v[220:223], v[72:75]
	v_mfma_f32_16x16x32_bf16 v[124:127], v[132:135], v[184:187], v[124:127]
	v_mfma_f32_16x16x32_bf16 v[120:123], v[140:143], v[184:187], v[120:123]
	v_mfma_f32_16x16x32_bf16 v[108:111], v[132:135], v[192:195], v[108:111]
	v_mfma_f32_16x16x32_bf16 v[104:107], v[140:143], v[192:195], v[104:107]
	v_mfma_f32_16x16x32_bf16 v[92:95], v[132:135], v[216:219], v[92:95]
	v_mfma_f32_16x16x32_bf16 v[88:91], v[140:143], v[216:219], v[88:91]
	v_mfma_f32_16x16x32_bf16 v[76:79], v[132:135], v[224:227], v[76:79]
	v_mfma_f32_16x16x32_bf16 v[72:75], v[140:143], v[224:227], v[72:75]
	v_mfma_f32_16x16x32_bf16 v[116:119], v[144:147], v[174:177], v[116:119]
	v_mfma_f32_16x16x32_bf16 v[112:115], v[152:155], v[174:177], v[112:115]
	v_mfma_f32_16x16x32_bf16 v[100:103], v[144:147], v[188:191], v[100:103]
	v_mfma_f32_16x16x32_bf16 v[96:99], v[152:155], v[188:191], v[96:99]
	v_mfma_f32_16x16x32_bf16 v[84:87], v[144:147], v[196:199], v[84:87]
	v_mfma_f32_16x16x32_bf16 v[80:83], v[152:155], v[196:199], v[80:83]
	v_mfma_f32_16x16x32_bf16 v[68:71], v[144:147], v[220:223], v[68:71]
	v_mfma_f32_16x16x32_bf16 v[64:67], v[152:155], v[220:223], v[64:67]
	v_mfma_f32_16x16x32_bf16 v[116:119], v[148:151], v[184:187], v[116:119]
	v_mfma_f32_16x16x32_bf16 v[112:115], v[156:159], v[184:187], v[112:115]
	v_mfma_f32_16x16x32_bf16 v[100:103], v[148:151], v[192:195], v[100:103]
	v_mfma_f32_16x16x32_bf16 v[96:99], v[156:159], v[192:195], v[96:99]
	v_mfma_f32_16x16x32_bf16 v[84:87], v[148:151], v[216:219], v[84:87]
	v_mfma_f32_16x16x32_bf16 v[80:83], v[156:159], v[216:219], v[80:83]
	v_mfma_f32_16x16x32_bf16 v[68:71], v[148:151], v[224:227], v[68:71]
	v_mfma_f32_16x16x32_bf16 v[64:67], v[156:159], v[224:227], v[64:67]
	s_barrier
; #define PG8_STAGE(bufoff, gbase, voff) do { _Pragma("unroll") for (int _i = 0; _i < 2; ++_i) \
;         __builtin_amdgcn_global_load_lds((const unsigned*)((const char*)(gbase) + (voff)[_i]), (PG8_LAS unsigned*)(lds + (bufoff) + ldsw + _i * 8192), 16, 0, 0); } while (0)
; #define PG8_LDA(dst, b, h) do { _Pragma("unroll") for (int m = 0; m < 4; ++m) _Pragma("unroll") for (int k = 0; k < 2; ++k) dst[m][k] = *(const PG8_LAS bf16x8*)(lds + PG8_SA(b, h) + aoff + m * 2048 + k * 1024); } while (0)
; #define PG8_MMA(ai, bj, At, Bt) do { __builtin_amdgcn_s_setprio(1); _Pragma("unroll") for (int m = 0; m < 4; ++m) _Pragma("unroll") for (int n = 0; n < 2; ++n) _Pragma("unroll") for (int k = 0; k < 2; ++k) \
;         acc[ai][bj][m][n] = __builtin_amdgcn_mfma_f32_16x16x32_bf16(Bt[n][k], At[m][k], acc[ai][bj][m][n], 0, 0, 0); __builtin_amdgcn_s_setprio(0); } while (0)
; #define PG8_WAIT_V(n) asm volatile("s_waitcnt vmcnt(" #n ")" ::: "memory")
; #define PG8_WAIT_L(n) asm volatile("s_waitcnt lgkmcnt(" #n ")" ::: "memory")
; #define PG8_BAR __builtin_amdgcn_s_barrier()
; #define PG8_SCHED __builtin_amdgcn_sched_barrier(0)
; template <class Epi, class Sched, bool ALIGN_EPI = false, bool SP2 = false>
; __device__ __forceinline__ void gemm_phase(PG8_LAS unsigned char* lds, const Gemm g, const Sched& S, const Epi& E) {
;     ...
;         for (int t = 0; t < nt; t += 2) {
;     ...
;             PG8_LDA(At, 1, 1); PG8_STAGE(PG8_SB(1, 0), b3, voffB); PG8_STAGE(PG8_SB(1, 1), b3 + hstep, voffB); PG8_STAGE(PG8_SA(1, 0), a3, voffA);
;             PG8_WAIT_V(8); PG8_WAIT_L(0); PG8_BAR; PG8_MMA(1, 0, At, B0); PG8_MMA(1, 1, At, B1); PG8_BAR; PG8_SCHED;
	s_setprio 1
	s_add_i32 s16, s16, s24
	v_lshl_add_u64 v[178:179], v[178:179], 0, s[58:59]
	s_mov_b32 m0, s16
	ds_read_b128 v[174:177], v215 offset:49152
	ds_read_b128 v[184:187], v215 offset:50176
	ds_read_b128 v[188:191], v215 offset:51200
	ds_read_b128 v[192:195], v215 offset:52224
	ds_read_b128 v[196:199], v215 offset:53248
	ds_read_b128 v[216:219], v215 offset:54272
	ds_read_b128 v[220:223], v215 offset:55296
	ds_read_b128 v[224:227], v215 offset:56320
	global_load_lds_dwordx4 v[178:179], off
	v_lshl_add_u64 v[178:179], v[200:201], 0, s[58:59]
	s_add_i32 m0, s16, 0x2000
	s_add_i32 s16, s34, s24
	global_load_lds_dwordx4 v[178:179], off
	v_lshl_add_u64 v[178:179], v[228:229], 0, s[58:59]
	s_mov_b32 m0, s16
	s_nop 0
	global_load_lds_dwordx4 v[178:179], off
	v_lshl_add_u64 v[178:179], v[230:231], 0, s[58:59]
	s_add_i32 m0, s16, 0x2000
	s_nop 0
	global_load_lds_dwordx4 v[178:179], off
	v_lshl_add_u64 v[178:179], v[232:233], 0, s[58:59]
	s_mov_b32 m0, s60
	s_nop 0
	global_load_lds_dwordx4 v[178:179], off
	v_lshl_add_u64 v[178:179], v[234:235], 0, s[58:59]
	s_mov_b32 m0, s61
	s_nop 0
	global_load_lds_dwordx4 v[178:179], off
	s_setprio 0
	s_waitcnt vmcnt(8)
	s_waitcnt lgkmcnt(0)
	s_barrier
	s_waitcnt lgkmcnt(0)
	v_mfma_f32_16x16x32_bf16 v[60:63], v[128:131], v[174:177], v[60:63]
	v_mfma_f32_16x16x32_bf16 v[56:59], v[136:139], v[174:177], v[56:59]
	v_mfma_f32_16x16x32_bf16 v[44:47], v[128:131], v[188:191], v[44:47]
	v_mfma_f32_16x16x32_bf16 v[40:43], v[136:139], v[188:191], v[40:43]
	v_mfma_f32_16x16x32_bf16 v[28:31], v[128:131], v[196:199], v[28:31]
	v_mfma_f32_16x16x32_bf16 v[24:27], v[136:139], v[196:199], v[24:27]
	v_mfma_f32_16x16x32_bf16 v[12:15], v[128:131], v[220:223], v[12:15]
	v_mfma_f32_16x16x32_bf16 v[8:11], v[136:139], v[220:223], v[8:11]
	v_mfma_f32_16x16x32_bf16 v[60:63], v[132:135], v[184:187], v[60:63]
	v_mfma_f32_16x16x32_bf16 v[56:59], v[140:143], v[184:187], v[56:59]
	v_mfma_f32_16x16x32_bf16 v[44:47], v[132:135], v[192:195], v[44:47]
	v_mfma_f32_16x16x32_bf16 v[40:43], v[140:143], v[192:195], v[40:43]
	v_mfma_f32_16x16x32_bf16 v[28:31], v[132:135], v[216:219], v[28:31]
	v_mfma_f32_16x16x32_bf16 v[24:27], v[140:143], v[216:219], v[24:27]
	v_mfma_f32_16x16x32_bf16 v[12:15], v[132:135], v[224:227], v[12:15]
	v_mfma_f32_16x16x32_bf16 v[8:11], v[140:143], v[224:227], v[8:11]
	v_mfma_f32_16x16x32_bf16 v[52:55], v[144:147], v[174:177], v[52:55]
	v_mfma_f32_16x16x32_bf16 v[48:51], v[152:155], v[174:177], v[48:51]
	v_mfma_f32_16x16x32_bf16 v[36:39], v[144:147], v[188:191], v[36:39]
	v_mfma_f32_16x16x32_bf16 v[32:35], v[152:155], v[188:191], v[32:35]
	v_mfma_f32_16x16x32_bf16 v[20:23], v[144:147], v[196:199], v[20:23]
	v_mfma_f32_16x16x32_bf16 v[16:19], v[152:155], v[196:199], v[16:19]
	v_mfma_f32_16x16x32_bf16 v[4:7], v[144:147], v[220:223], v[4:7]
	v_mfma_f32_16x16x32_bf16 v[0:3], v[152:155], v[220:223], v[0:3]
	v_mfma_f32_16x16x32_bf16 v[52:55], v[148:151], v[184:187], v[52:55]
	v_mfma_f32_16x16x32_bf16 v[48:51], v[156:159], v[184:187], v[48:51]
	v_mfma_f32_16x16x32_bf16 v[36:39], v[148:151], v[192:195], v[36:39]
	v_mfma_f32_16x16x32_bf16 v[32:35], v[156:159], v[192:195], v[32:35]
	v_mfma_f32_16x16x32_bf16 v[20:23], v[148:151], v[216:219], v[20:23]
	v_mfma_f32_16x16x32_bf16 v[16:19], v[156:159], v[216:219], v[16:19]
	v_mfma_f32_16x16x32_bf16 v[4:7], v[148:151], v[224:227], v[4:7]
	v_mfma_f32_16x16x32_bf16 v[0:3], v[156:159], v[224:227], v[0:3]
	s_barrier
	s_setprio 1
	s_add_u32 s6, s6, 0x100
	s_addc_u32 s7, s7, 0
	s_add_u32 s50, s50, 0x100
	s_addc_u32 s79, s79, 0
	s_cmp_ge_u32 s97, s26
	s_mov_b32 s42, s97
	s_cbranch_scc0 .LBB0_890
	s_and_b64 vcc, exec, s[30:31]
	s_cbranch_vccz .LBB0_893
	s_barrier

; #define PG8_STAGE(bufoff, gbase, voff) do { _Pragma("unroll") for (int _i = 0; _i < 2; ++_i) \
;         __builtin_amdgcn_global_load_lds((const unsigned*)((const char*)(gbase) + (voff)[_i]), (PG8_LAS unsigned*)(lds + (bufoff) + ldsw + _i * 8192), 16, 0, 0); } while (0)
; #define PG8_LDA(dst, b, h) do { _Pragma("unroll") for (int m = 0; m < 4; ++m) _Pragma("unroll") for (int k = 0; k < 2; ++k) dst[m][k] = *(const PG8_LAS bf16x8*)(lds + PG8_SA(b, h) + aoff + m * 2048 + k * 1024); } while (0)
; #define PG8_LDB(dst, b, h) do { _Pragma("unroll") for (int n = 0; n < 2; ++n) _Pragma("unroll") for (int k = 0; k < 2; ++k) dst[n][k] = *(const PG8_LAS bf16x8*)(lds + PG8_SB(b, h) + boff + n * 2048 + k * 1024); } while (0)
; #define PG8_MMA(ai, bj, At, Bt) do { __builtin_amdgcn_s_setprio(1); _Pragma("unroll") for (int m = 0; m < 4; ++m) _Pragma("unroll") for (int n = 0; n < 2; ++n) _Pragma("unroll") for (int k = 0; k < 2; ++k) \
;         acc[ai][bj][m][n] = __builtin_amdgcn_mfma_f32_16x16x32_bf16(Bt[n][k], At[m][k], acc[ai][bj][m][n], 0, 0, 0); __builtin_amdgcn_s_setprio(0); } while (0)
; #define PG8_WAIT_V(n) asm volatile("s_waitcnt vmcnt(" #n ")" ::: "memory")
; #define PG8_WAIT_L(n) asm volatile("s_waitcnt lgkmcnt(" #n ")" ::: "memory")
; template <class Epi, class Sched, bool ALIGN_EPI = false, bool SP2 = false>
; __device__ __forceinline__ void gemm_phase(PG8_LAS unsigned char* lds, const Gemm g, const Sched& S, const Epi& E) {
;     ...
;             const bool last = (t == nt - 2);
;             const char* a1 = cA + (size_t)(t + 1) * kstep;
;             const char* a2 = last ? nA : cA + (size_t)(t + 2) * kstep; const char* b2 = last ? nB : cB + (size_t)(t + 2) * kstep;
;             const char* a3 = a2 + kstep; const char* b3 = b2 + kstep;
;             if (last && has_next) S.a_ready(nxt);
;             if constexpr (SP2) {
;             PG8_LDB(B0, 0, 0); PG8_LDB(B1, 0, 1); PG8_SCHED; PG8_LDA(At, 0, 0); PG8_STAGE(PG8_SA(1, 1), a1 + hstep, voffA);
;             PG8_WAIT_V(8); PG8_WAIT_L(0); PG8_BAR; PG8_MMA(0, 0, At, B0); PG8_MMA(0, 1, At, B1); PG8_BAR; PG8_SCHED;
;             PG8_LDA(At, 0, 1); PG8_STAGE(PG8_SB(0, 0), b2, voffB); PG8_STAGE(PG8_SB(0, 1), b2 + hstep, voffB); PG8_STAGE(PG8_SA(0, 0), a2, voffA);
;             PG8_WAIT_V(8); PG8_WAIT_L(0); PG8_BAR; PG8_MMA(1, 0, At, B0); PG8_MMA(1, 1, At, B1); PG8_BAR; PG8_SCHED;
.LBB0_1067:
	s_add_u32 s16, s6, 0xfffc0080
	s_addc_u32 s34, s7, -1
	s_add_i32 s35, 0, 0x10000
	s_cmp_eq_u32 s47, 12
	s_cselect_b32 s53, s25, s34
	s_cselect_b32 s52, s26, s16
	v_add_u32_e32 v147, s35, v145
	s_cselect_b32 s49, s27, s45
	s_cselect_b32 s48, s29, s31
	s_add_i32 s16, 0, 0x14000
	ds_read_b128 v[140:143], v147
	ds_read_b128 v[148:151], v147 offset:1024
	ds_read_b128 v[152:155], v147 offset:2048
	ds_read_b128 v[156:159], v147 offset:3072
	v_add_u32_e32 v147, s16, v145
	ds_read_b128 v[160:163], v147
	ds_read_b128 v[164:167], v147 offset:1024
	ds_read_b128 v[168:171], v147 offset:2048
	ds_read_b128 v[172:175], v147 offset:3072
	v_lshl_add_u64 v[200:201], s[6:7], 0, v[136:137]
	s_add_i32 m0, s15, 0xc000
	ds_read_b128 v[176:179], v146
	ds_read_b128 v[184:187], v146 offset:1024
	ds_read_b128 v[188:191], v146 offset:2048
	ds_read_b128 v[192:195], v146 offset:3072
	ds_read_b128 v[196:199], v146 offset:4096
	ds_read_b128 v[210:213], v146 offset:5120
	ds_read_b128 v[214:217], v146 offset:6144
	ds_read_b128 v[218:221], v146 offset:7168
	global_load_lds_dwordx4 v[200:201], off
	v_lshl_add_u64 v[200:201], s[6:7], 0, v[138:139]
	s_add_i32 m0, s15, 0xe000
	s_nop 0
	global_load_lds_dwordx4 v[200:201], off
	s_setprio 0
	s_waitcnt vmcnt(8)
	s_waitcnt lgkmcnt(0)
	s_barrier
	s_waitcnt lgkmcnt(0)
	v_mfma_f32_16x16x32_bf16 v[124:127], v[140:143], v[176:179], v[124:127]
	v_mfma_f32_16x16x32_bf16 v[120:123], v[152:155], v[176:179], v[120:123]
	v_mfma_f32_16x16x32_bf16 v[108:111], v[140:143], v[188:191], v[108:111]
	v_mfma_f32_16x16x32_bf16 v[104:107], v[152:155], v[188:191], v[104:107]
	v_mfma_f32_16x16x32_bf16 v[92:95], v[140:143], v[196:199], v[92:95]
	v_mfma_f32_16x16x32_bf16 v[88:91], v[152:155], v[196:199], v[88:91]
	v_mfma_f32_16x16x32_bf16 v[76:79], v[140:143], v[214:217], v[76:79]
	v_mfma_f32_16x16x32_bf16 v[72:75], v[152:155], v[214:217], v[72:75]
	v_mfma_f32_16x16x32_bf16 v[124:127], v[148:151], v[184:187], v[124:127]
	v_mfma_f32_16x16x32_bf16 v[120:123], v[156:159], v[184:187], v[120:123]
	v_mfma_f32_16x16x32_bf16 v[108:111], v[148:151], v[192:195], v[108:111]
	v_mfma_f32_16x16x32_bf16 v[104:107], v[156:159], v[192:195], v[104:107]
	v_mfma_f32_16x16x32_bf16 v[92:95], v[148:151], v[210:213], v[92:95]
	v_mfma_f32_16x16x32_bf16 v[88:91], v[156:159], v[210:213], v[88:91]
	v_mfma_f32_16x16x32_bf16 v[76:79], v[148:151], v[218:221], v[76:79]
	v_mfma_f32_16x16x32_bf16 v[72:75], v[156:159], v[218:221], v[72:75]
	v_mfma_f32_16x16x32_bf16 v[116:119], v[160:163], v[176:179], v[116:119]
	v_mfma_f32_16x16x32_bf16 v[112:115], v[168:171], v[176:179], v[112:115]
	v_mfma_f32_16x16x32_bf16 v[100:103], v[160:163], v[188:191], v[100:103]
	v_mfma_f32_16x16x32_bf16 v[96:99], v[168:171], v[188:191], v[96:99]
	v_mfma_f32_16x16x32_bf16 v[84:87], v[160:163], v[196:199], v[84:87]
	v_mfma_f32_16x16x32_bf16 v[80:83], v[168:171], v[196:199], v[80:83]
	v_mfma_f32_16x16x32_bf16 v[68:71], v[160:163], v[214:217], v[68:71]
	v_mfma_f32_16x16x32_bf16 v[64:67], v[168:171], v[214:217], v[64:67]
	v_mfma_f32_16x16x32_bf16 v[116:119], v[164:167], v[184:187], v[116:119]
	v_mfma_f32_16x16x32_bf16 v[112:115], v[172:175], v[184:187], v[112:115]
	v_mfma_f32_16x16x32_bf16 v[100:103], v[164:167], v[192:195], v[100:103]
	v_mfma_f32_16x16x32_bf16 v[96:99], v[172:175], v[192:195], v[96:99]
	v_mfma_f32_16x16x32_bf16 v[84:87], v[164:167], v[210:213], v[84:87]
	v_mfma_f32_16x16x32_bf16 v[80:83], v[172:175], v[210:213], v[80:83]
	v_mfma_f32_16x16x32_bf16 v[68:71], v[164:167], v[218:221], v[68:71]
	v_mfma_f32_16x16x32_bf16 v[64:67], v[172:175], v[218:221], v[64:67]
	s_barrier
	s_setprio 1
	s_add_i32 s34, s35, s13
	v_lshl_add_u64 v[200:201], s[48:49], 0, v[130:131]
	s_mov_b32 m0, s34
	ds_read_b128 v[176:179], v146 offset:16384
	ds_read_b128 v[184:187], v146 offset:17408
	ds_read_b128 v[188:191], v146 offset:18432
	ds_read_b128 v[192:195], v146 offset:19456
	ds_read_b128 v[196:199], v146 offset:20480
	ds_read_b128 v[210:213], v146 offset:21504
	ds_read_b128 v[214:217], v146 offset:22528
	ds_read_b128 v[218:221], v146 offset:23552
	global_load_lds_dwordx4 v[200:201], off
	s_add_i32 m0, s34, 0x2000
	s_add_u32 s34, s48, 0x40000
	v_lshl_add_u64 v[222:223], s[48:49], 0, v[134:135]
	s_addc_u32 s35, s49, 0
	s_add_i32 s16, s16, s13
	global_load_lds_dwordx4 v[222:223], off
	v_lshl_add_u64 v[224:225], s[34:35], 0, v[130:131]
	s_mov_b32 m0, s16
	v_lshl_add_u64 v[226:227], s[52:53], 0, v[132:133]
	global_load_lds_dwordx4 v[224:225], off
	v_lshl_add_u64 v[224:225], s[34:35], 0, v[134:135]
	s_add_i32 m0, s16, 0x2000
	s_nop 0
	global_load_lds_dwordx4 v[224:225], off
	v_lshl_add_u64 v[224:225], s[52:53], 0, v[128:129]
	s_mov_b32 m0, s15
	s_nop 0
	global_load_lds_dwordx4 v[224:225], off
	s_mov_b32 m0, s19
	s_nop 0
	global_load_lds_dwordx4 v[226:227], off
	s_setprio 0
	s_waitcnt vmcnt(8)
	s_waitcnt lgkmcnt(0)
	s_barrier
; #define PG8_STAGE(bufoff, gbase, voff) do { _Pragma("unroll") for (int _i = 0; _i < 2; ++_i) \
;         __builtin_amdgcn_global_load_lds((const unsigned*)((const char*)(gbase) + (voff)[_i]), (PG8_LAS unsigned*)(lds + (bufoff) + ldsw + _i * 8192), 16, 0, 0); } while (0)
; #define PG8_LDA(dst, b, h) do { _Pragma("unroll") for (int m = 0; m < 4; ++m) _Pragma("unroll") for (int k = 0; k < 2; ++k) dst[m][k] = *(const PG8_LAS bf16x8*)(lds + PG8_SA(b, h) + aoff + m * 2048 + k * 1024); } while (0)
; #define PG8_LDB(dst, b, h) do { _Pragma("unroll") for (int n = 0; n < 2; ++n) _Pragma("unroll") for (int k = 0; k < 2; ++k) dst[n][k] = *(const PG8_LAS bf16x8*)(lds + PG8_SB(b, h) + boff + n * 2048 + k * 1024); } while (0)
; #define PG8_MMA(ai, bj, At, Bt) do { __builtin_amdgcn_s_setprio(1); _Pragma("unroll") for (int m = 0; m < 4; ++m) _Pragma("unroll") for (int n = 0; n < 2; ++n) _Pragma("unroll") for (int k = 0; k < 2; ++k) \
;         acc[ai][bj][m][n] = __builtin_amdgcn_mfma_f32_16x16x32_bf16(Bt[n][k], At[m][k], acc[ai][bj][m][n], 0, 0, 0); __builtin_amdgcn_s_setprio(0); } while (0)
; #define PG8_WAIT_V(n) asm volatile("s_waitcnt vmcnt(" #n ")" ::: "memory")
; #define PG8_WAIT_L(n) asm volatile("s_waitcnt lgkmcnt(" #n ")" ::: "memory")
; #define PG8_BAR __builtin_amdgcn_s_barrier()
; #define PG8_SCHED __builtin_amdgcn_sched_barrier(0)
; template <class Epi, class Sched, bool ALIGN_EPI = false, bool SP2 = false>
; __device__ __forceinline__ void gemm_phase(PG8_LAS unsigned char* lds, const Gemm g, const Sched& S, const Epi& E) {
;     ...
;             PG8_WAIT_V(8); PG8_WAIT_L(0); PG8_BAR; PG8_MMA(1, 0, At, B0); PG8_MMA(1, 1, At, B1); PG8_BAR; PG8_SCHED;
;             PG8_LDB(B0, 1, 0); PG8_LDB(B1, 1, 1); PG8_SCHED; PG8_LDA(At, 1, 0); PG8_STAGE(PG8_SA(0, 1), a2 + hstep, voffA);
;             PG8_WAIT_V(8); PG8_WAIT_L(0); PG8_BAR; PG8_MMA(0, 0, At, B0); PG8_MMA(0, 1, At, B1); PG8_BAR; PG8_SCHED;
;             PG8_LDA(At, 1, 1); PG8_STAGE(PG8_SB(1, 0), b3, voffB); PG8_STAGE(PG8_SB(1, 1), b3 + hstep, voffB); PG8_STAGE(PG8_SA(1, 0), a3, voffA);
;             PG8_WAIT_V(8); PG8_WAIT_L(0); PG8_BAR; PG8_MMA(1, 0, At, B0); PG8_MMA(1, 1, At, B1); PG8_BAR; PG8_SCHED;
	s_waitcnt lgkmcnt(0)
	v_mfma_f32_16x16x32_bf16 v[60:63], v[140:143], v[176:179], v[60:63]
	v_mfma_f32_16x16x32_bf16 v[56:59], v[152:155], v[176:179], v[56:59]
	v_mfma_f32_16x16x32_bf16 v[44:47], v[140:143], v[188:191], v[44:47]
	v_mfma_f32_16x16x32_bf16 v[40:43], v[152:155], v[188:191], v[40:43]
	v_mfma_f32_16x16x32_bf16 v[28:31], v[140:143], v[196:199], v[28:31]
	v_mfma_f32_16x16x32_bf16 v[24:27], v[152:155], v[196:199], v[24:27]
	v_mfma_f32_16x16x32_bf16 v[12:15], v[140:143], v[214:217], v[12:15]
	v_mfma_f32_16x16x32_bf16 v[8:11], v[152:155], v[214:217], v[8:11]
	v_mfma_f32_16x16x32_bf16 v[60:63], v[148:151], v[184:187], v[60:63]
	v_mfma_f32_16x16x32_bf16 v[56:59], v[156:159], v[184:187], v[56:59]
	v_mfma_f32_16x16x32_bf16 v[44:47], v[148:151], v[192:195], v[44:47]
	v_mfma_f32_16x16x32_bf16 v[40:43], v[156:159], v[192:195], v[40:43]
	v_mfma_f32_16x16x32_bf16 v[28:31], v[148:151], v[210:213], v[28:31]
	v_mfma_f32_16x16x32_bf16 v[24:27], v[156:159], v[210:213], v[24:27]
	v_mfma_f32_16x16x32_bf16 v[12:15], v[148:151], v[218:221], v[12:15]
	v_mfma_f32_16x16x32_bf16 v[8:11], v[156:159], v[218:221], v[8:11]
	v_mfma_f32_16x16x32_bf16 v[52:55], v[160:163], v[176:179], v[52:55]
	v_mfma_f32_16x16x32_bf16 v[48:51], v[168:171], v[176:179], v[48:51]
	v_mfma_f32_16x16x32_bf16 v[36:39], v[160:163], v[188:191], v[36:39]
	v_mfma_f32_16x16x32_bf16 v[32:35], v[168:171], v[188:191], v[32:35]
	v_mfma_f32_16x16x32_bf16 v[20:23], v[160:163], v[196:199], v[20:23]
	v_mfma_f32_16x16x32_bf16 v[16:19], v[168:171], v[196:199], v[16:19]
	v_mfma_f32_16x16x32_bf16 v[4:7], v[160:163], v[214:217], v[4:7]
	v_mfma_f32_16x16x32_bf16 v[0:3], v[168:171], v[214:217], v[0:3]
	v_mfma_f32_16x16x32_bf16 v[52:55], v[164:167], v[184:187], v[52:55]
	v_mfma_f32_16x16x32_bf16 v[48:51], v[172:175], v[184:187], v[48:51]
	v_mfma_f32_16x16x32_bf16 v[36:39], v[164:167], v[192:195], v[36:39]
	v_mfma_f32_16x16x32_bf16 v[32:35], v[172:175], v[192:195], v[32:35]
	v_mfma_f32_16x16x32_bf16 v[20:23], v[164:167], v[210:213], v[20:23]
	v_mfma_f32_16x16x32_bf16 v[16:19], v[172:175], v[210:213], v[16:19]
	v_mfma_f32_16x16x32_bf16 v[4:7], v[164:167], v[218:221], v[4:7]
	v_mfma_f32_16x16x32_bf16 v[0:3], v[172:175], v[218:221], v[0:3]
	s_barrier
	s_setprio 1
	s_add_i32 s16, 0, 0x18000
	v_add_u32_e32 v147, s16, v145
	s_add_i32 s60, 0, 0x1c000
	ds_read_b128 v[140:143], v147
	ds_read_b128 v[148:151], v147 offset:1024
	ds_read_b128 v[152:155], v147 offset:2048
	ds_read_b128 v[156:159], v147 offset:3072
	v_add_u32_e32 v147, s60, v145
	ds_read_b128 v[160:163], v147
	ds_read_b128 v[164:167], v147 offset:1024
	ds_read_b128 v[168:171], v147 offset:2048
	ds_read_b128 v[172:175], v147 offset:3072
	s_add_u32 s34, s52, 0x40000
	s_addc_u32 s35, s53, 0
	s_mov_b32 m0, s20
	v_lshl_add_u64 v[228:229], s[34:35], 0, v[128:129]
	ds_read_b128 v[176:179], v146 offset:32768
	ds_read_b128 v[184:187], v146 offset:33792
	ds_read_b128 v[188:191], v146 offset:34816
	ds_read_b128 v[192:195], v146 offset:35840
	ds_read_b128 v[196:199], v146 offset:36864
	ds_read_b128 v[210:213], v146 offset:37888
	ds_read_b128 v[214:217], v146 offset:38912
	ds_read_b128 v[218:221], v146 offset:39936
	global_load_lds_dwordx4 v[228:229], off
	v_lshl_add_u64 v[228:229], s[34:35], 0, v[132:133]
	s_mov_b32 m0, s21
	s_nop 0
	global_load_lds_dwordx4 v[228:229], off
	s_setprio 0
	s_waitcnt vmcnt(8)
	s_waitcnt lgkmcnt(0)
	s_barrier
	s_waitcnt lgkmcnt(0)
	v_mfma_f32_16x16x32_bf16 v[124:127], v[140:143], v[176:179], v[124:127]
	v_mfma_f32_16x16x32_bf16 v[120:123], v[152:155], v[176:179], v[120:123]
	v_mfma_f32_16x16x32_bf16 v[108:111], v[140:143], v[188:191], v[108:111]
	v_mfma_f32_16x16x32_bf16 v[104:107], v[152:155], v[188:191], v[104:107]
	v_mfma_f32_16x16x32_bf16 v[92:95], v[140:143], v[196:199], v[92:95]
	v_mfma_f32_16x16x32_bf16 v[88:91], v[152:155], v[196:199], v[88:91]
	v_mfma_f32_16x16x32_bf16 v[76:79], v[140:143], v[214:217], v[76:79]
	v_mfma_f32_16x16x32_bf16 v[72:75], v[152:155], v[214:217], v[72:75]
	v_mfma_f32_16x16x32_bf16 v[124:127], v[148:151], v[184:187], v[124:127]
	v_mfma_f32_16x16x32_bf16 v[120:123], v[156:159], v[184:187], v[120:123]
	v_mfma_f32_16x16x32_bf16 v[108:111], v[148:151], v[192:195], v[108:111]
	v_mfma_f32_16x16x32_bf16 v[104:107], v[156:159], v[192:195], v[104:107]
	v_mfma_f32_16x16x32_bf16 v[92:95], v[148:151], v[210:213], v[92:95]
	v_mfma_f32_16x16x32_bf16 v[88:91], v[156:159], v[210:213], v[88:91]
	v_mfma_f32_16x16x32_bf16 v[76:79], v[148:151], v[218:221], v[76:79]
	v_mfma_f32_16x16x32_bf16 v[72:75], v[156:159], v[218:221], v[72:75]
	v_mfma_f32_16x16x32_bf16 v[116:119], v[160:163], v[176:179], v[116:119]
	v_mfma_f32_16x16x32_bf16 v[112:115], v[168:171], v[176:179], v[112:115]
	v_mfma_f32_16x16x32_bf16 v[100:103], v[160:163], v[188:191], v[100:103]
	v_mfma_f32_16x16x32_bf16 v[96:99], v[168:171], v[188:191], v[96:99]
	v_mfma_f32_16x16x32_bf16 v[84:87], v[160:163], v[196:199], v[84:87]
	v_mfma_f32_16x16x32_bf16 v[80:83], v[168:171], v[196:199], v[80:83]
	v_mfma_f32_16x16x32_bf16 v[68:71], v[160:163], v[214:217], v[68:71]
	v_mfma_f32_16x16x32_bf16 v[64:67], v[168:171], v[214:217], v[64:67]
	v_mfma_f32_16x16x32_bf16 v[116:119], v[164:167], v[184:187], v[116:119]
	v_mfma_f32_16x16x32_bf16 v[112:115], v[172:175], v[184:187], v[112:115]
	v_mfma_f32_16x16x32_bf16 v[100:103], v[164:167], v[192:195], v[100:103]
	v_mfma_f32_16x16x32_bf16 v[96:99], v[172:175], v[192:195], v[96:99]
	v_mfma_f32_16x16x32_bf16 v[84:87], v[164:167], v[210:213], v[84:87]
	v_mfma_f32_16x16x32_bf16 v[80:83], v[172:175], v[210:213], v[80:83]
	v_mfma_f32_16x16x32_bf16 v[68:71], v[164:167], v[218:221], v[68:71]
	v_mfma_f32_16x16x32_bf16 v[64:67], v[172:175], v[218:221], v[64:67]
	s_barrier
; #define PG8_STAGE(bufoff, gbase, voff) do { _Pragma("unroll") for (int _i = 0; _i < 2; ++_i) \
;         __builtin_amdgcn_global_load_lds((const unsigned*)((const char*)(gbase) + (voff)[_i]), (PG8_LAS unsigned*)(lds + (bufoff) + ldsw + _i * 8192), 16, 0, 0); } while (0)
; #define PG8_LDA(dst, b, h) do { _Pragma("unroll") for (int m = 0; m < 4; ++m) _Pragma("unroll") for (int k = 0; k < 2; ++k) dst[m][k] = *(const PG8_LAS bf16x8*)(lds + PG8_SA(b, h) + aoff + m * 2048 + k * 1024); } while (0)
; #define PG8_MMA(ai, bj, At, Bt) do { __builtin_amdgcn_s_setprio(1); _Pragma("unroll") for (int m = 0; m < 4; ++m) _Pragma("unroll") for (int n = 0; n < 2; ++n) _Pragma("unroll") for (int k = 0; k < 2; ++k) \
;         acc[ai][bj][m][n] = __builtin_amdgcn_mfma_f32_16x16x32_bf16(Bt[n][k], At[m][k], acc[ai][bj][m][n], 0, 0, 0); __builtin_amdgcn_s_setprio(0); } while (0)
; #define PG8_WAIT_V(n) asm volatile("s_waitcnt vmcnt(" #n ")" ::: "memory")
; #define PG8_WAIT_L(n) asm volatile("s_waitcnt lgkmcnt(" #n ")" ::: "memory")
; #define PG8_BAR __builtin_amdgcn_s_barrier()
; #define PG8_SCHED __builtin_amdgcn_sched_barrier(0)
; template <class Epi, class Sched, bool ALIGN_EPI = false, bool SP2 = false>
; __device__ __forceinline__ void gemm_phase(PG8_LAS unsigned char* lds, const Gemm g, const Sched& S, const Epi& E) {
;     ...
;         for (int t = 0; t < nt; t += 2) {
;     ...
;             PG8_LDA(At, 1, 1); PG8_STAGE(PG8_SB(1, 0), b3, voffB); PG8_STAGE(PG8_SB(1, 1), b3 + hstep, voffB); PG8_STAGE(PG8_SA(1, 0), a3, voffA);
;             PG8_WAIT_V(8); PG8_WAIT_L(0); PG8_BAR; PG8_MMA(1, 0, At, B0); PG8_MMA(1, 1, At, B1); PG8_BAR; PG8_SCHED;
	s_setprio 1
	s_add_i32 s16, s16, s13
	v_lshl_add_u64 v[200:201], v[200:201], 0, s[58:59]
	s_mov_b32 m0, s16
	ds_read_b128 v[176:179], v146 offset:49152
	ds_read_b128 v[184:187], v146 offset:50176
	ds_read_b128 v[188:191], v146 offset:51200
	ds_read_b128 v[192:195], v146 offset:52224
	ds_read_b128 v[196:199], v146 offset:53248
	ds_read_b128 v[210:213], v146 offset:54272
	ds_read_b128 v[214:217], v146 offset:55296
	ds_read_b128 v[218:221], v146 offset:56320
	global_load_lds_dwordx4 v[200:201], off
	s_add_i32 m0, s16, 0x2000
	s_add_u32 s34, s48, 0x40080
	v_lshl_add_u64 v[200:201], v[222:223], 0, s[58:59]
	s_addc_u32 s35, s49, 0
	s_add_i32 s16, s60, s13
	global_load_lds_dwordx4 v[200:201], off
	v_lshl_add_u64 v[200:201], s[34:35], 0, v[130:131]
	s_mov_b32 m0, s16
	s_nop 0
	global_load_lds_dwordx4 v[200:201], off
	v_lshl_add_u64 v[200:201], s[34:35], 0, v[134:135]
	s_add_i32 m0, s16, 0x2000
	s_nop 0
	global_load_lds_dwordx4 v[200:201], off
	v_lshl_add_u64 v[200:201], v[224:225], 0, s[58:59]
	s_mov_b32 m0, s22
	s_nop 0
	global_load_lds_dwordx4 v[200:201], off
	v_lshl_add_u64 v[200:201], v[226:227], 0, s[58:59]
	s_mov_b32 m0, s23
	s_nop 0
	global_load_lds_dwordx4 v[200:201], off
	s_setprio 0
	s_waitcnt vmcnt(8)
	s_waitcnt lgkmcnt(0)
	s_barrier
	s_waitcnt lgkmcnt(0)
	v_mfma_f32_16x16x32_bf16 v[60:63], v[140:143], v[176:179], v[60:63]
	v_mfma_f32_16x16x32_bf16 v[56:59], v[152:155], v[176:179], v[56:59]
	v_mfma_f32_16x16x32_bf16 v[44:47], v[140:143], v[188:191], v[44:47]
	v_mfma_f32_16x16x32_bf16 v[40:43], v[152:155], v[188:191], v[40:43]
	v_mfma_f32_16x16x32_bf16 v[28:31], v[140:143], v[196:199], v[28:31]
	v_mfma_f32_16x16x32_bf16 v[24:27], v[152:155], v[196:199], v[24:27]
	v_mfma_f32_16x16x32_bf16 v[12:15], v[140:143], v[214:217], v[12:15]
	v_mfma_f32_16x16x32_bf16 v[8:11], v[152:155], v[214:217], v[8:11]
	v_mfma_f32_16x16x32_bf16 v[60:63], v[148:151], v[184:187], v[60:63]
	v_mfma_f32_16x16x32_bf16 v[56:59], v[156:159], v[184:187], v[56:59]
	v_mfma_f32_16x16x32_bf16 v[44:47], v[148:151], v[192:195], v[44:47]
	v_mfma_f32_16x16x32_bf16 v[40:43], v[156:159], v[192:195], v[40:43]
	v_mfma_f32_16x16x32_bf16 v[28:31], v[148:151], v[210:213], v[28:31]
	v_mfma_f32_16x16x32_bf16 v[24:27], v[156:159], v[210:213], v[24:27]
	v_mfma_f32_16x16x32_bf16 v[12:15], v[148:151], v[218:221], v[12:15]
	v_mfma_f32_16x16x32_bf16 v[8:11], v[156:159], v[218:221], v[8:11]
	v_mfma_f32_16x16x32_bf16 v[52:55], v[160:163], v[176:179], v[52:55]
	v_mfma_f32_16x16x32_bf16 v[48:51], v[168:171], v[176:179], v[48:51]
	v_mfma_f32_16x16x32_bf16 v[36:39], v[160:163], v[188:191], v[36:39]
	v_mfma_f32_16x16x32_bf16 v[32:35], v[168:171], v[188:191], v[32:35]
	v_mfma_f32_16x16x32_bf16 v[20:23], v[160:163], v[196:199], v[20:23]
	v_mfma_f32_16x16x32_bf16 v[16:19], v[168:171], v[196:199], v[16:19]
	v_mfma_f32_16x16x32_bf16 v[4:7], v[160:163], v[214:217], v[4:7]
	v_mfma_f32_16x16x32_bf16 v[0:3], v[168:171], v[214:217], v[0:3]
	v_mfma_f32_16x16x32_bf16 v[52:55], v[164:167], v[184:187], v[52:55]
	v_mfma_f32_16x16x32_bf16 v[48:51], v[172:175], v[184:187], v[48:51]
	v_mfma_f32_16x16x32_bf16 v[36:39], v[164:167], v[192:195], v[36:39]
	v_mfma_f32_16x16x32_bf16 v[32:35], v[172:175], v[192:195], v[32:35]
	v_mfma_f32_16x16x32_bf16 v[20:23], v[164:167], v[210:213], v[20:23]
	v_mfma_f32_16x16x32_bf16 v[16:19], v[172:175], v[210:213], v[16:19]
	v_mfma_f32_16x16x32_bf16 v[4:7], v[164:167], v[218:221], v[4:7]
	v_mfma_f32_16x16x32_bf16 v[0:3], v[172:175], v[218:221], v[0:3]
	s_barrier
	s_setprio 1
	s_add_i32 s47, s47, 2
	s_add_u32 s6, s6, 0x100
	s_addc_u32 s7, s7, 0
	s_add_u32 s31, s31, 0x100
	s_addc_u32 s45, s45, 0
	s_cmp_gt_u32 s47, 13
	s_cbranch_scc0 .LBB0_1067
	s_and_b64 vcc, exec, s[4:5]
	s_cbranch_vccz .LBB0_1070
	s_barrier
